# seq operand loads (Q,C,X,B) remapped so each load pair covers whole 128B lines; matching LDS read offsets
# baseline (speedup 1.0000x reference)
; __device__ void gla_seq(const KP& p, int l, int s, int h, int vq) {
;     ...
;   const unsigned qoff = (unsigned)(((ti * 16 + fr) * NIN + 1536 + h * 128 + fq * 8) * 2);
;   const unsigned koff = (unsigned)((((kA >> 2)) * NIN + 2048 + h * 128 + (kA & 3) * 32 + fq * 8) * 2);
;   unsigned voff[2];
; #pragma unroll
;   for (int vt = 0; vt < 2; ++vt) { int _v = vq * 32 + vt * 16 + fr; voff[vt] = (unsigned)(((_v >> 2) * NIN + 2560 + h * 128 + (_v & 3) * 32 + fq * 8) * 2); }
;   const unsigned ooff = (unsigned)(((ti * 16 + fq * 4) * DM + oc) * 2);
;   const unsigned doff = (unsigned)((h * 128 + 16 * w + fq * 4) * 4);
;     ...
; #pragma unroll
;   for (int k = 0; k < 4; ++k) GLA_LOAD(k, min(k, nst - 1));
.LBB0_348:
	v_lshrrev_b32_e32 v3, 3, v0
	s_waitcnt vmcnt(0)
	v_cvt_pk_bf16_f32 v2, v25, s0
	v_and_b32_e32 v3, 16, v3
	ds_write_b16 v5, v2 offset:6
	v_or_b32_e32 v5, v3, v175
	s_lshl_b32 s56, s56, 7
	v_or_b32_e32 v2, v151, v175
	v_mul_u32_u24_e32 v5, 0xe00, v5
	v_lshlrev_b32_e32 v174, 3, v4
	v_or3_b32 v4, v5, s56, v174
	v_lshrrev_b32_e32 v2, 2, v2
	s_movk_i32 s58, 0xe00
	v_lshlrev_b32_e32 v0, 5, v0
	v_or_b32_e32 v5, s3, v175
	v_mul_lo_u32 v2, v2, s58
	v_and_b32_e32 v0, 0x60, v0
	v_lshrrev_b32_e32 v5, 2, v5
	v_or_b32_e32 v2, v2, v0
	v_mul_u32_u24_e32 v5, 0xe00, v5
	v_or_b32_e32 v0, s56, v0
	s_or_b32 s57, s3, s56
	v_and_b32_e32 v195, 16, v151
	v_or3_b32 v2, v2, s56, v174
	v_or3_b32 v0, v0, v174, v5
	v_lshl_add_u32 v150, v4, 1, v173
	v_lshl_add_u32 v150, v174, 1, v150
	v_mov_b32_e32 v4, 0x1000
	v_or_b32_e32 v141, v153, v3
	v_lshl_add_u32 v8, v0, 1, v165
	v_or3_b32 v0, s57, v175, v195
	v_lshl_add_u32 v152, v2, 1, v4
	v_lshlrev_b32_e32 v2, 11, v141
	v_readlane_b32 s16, v255, 45
	v_lshl_or_b32 v0, v0, 1, v2
	v_readlane_b32 s17, v255, 46
	v_add_u32_e32 v2, s56, v151
	s_add_i32 s3, s2, -1
	v_lshl_add_u64 v[4:5], s[16:17], 0, v[0:1]
	s_mov_b64 s[56:57], 0x12a29400
	s_mul_i32 s60, s72, 0x1c00
	v_or_b32_e32 v2, v2, v153
	v_lshl_add_u64 v[148:149], v[4:5], 0, s[56:57]
	s_mul_hi_u32 s57, s72, 0x1c00
	s_add_u32 s56, s36, s60
	v_lshlrev_b32_e32 v2, 2, v2
	v_mov_b32_e32 v3, v1
	s_addc_u32 s57, s37, s57
	s_lshl_b64 s[58:59], s[72:73], 11
	v_lshl_add_u64 v[154:155], s[50:51], 0, v[2:3]
	v_lshl_add_u64 v[2:3], v[148:149], 0, s[58:59]
	s_waitcnt lgkmcnt(0)
	s_barrier
	global_load_dwordx4 v[134:137], v150, s[56:57]
	global_load_dwordx4 v[130:133], v150, s[56:57] offset:16
	global_load_dwordx4 v[126:129], v150, s[56:57] offset:128
	global_load_dwordx4 v[122:125], v150, s[56:57] offset:144
	global_load_ushort v193, v[2:3], off
	global_load_ushort v192, v[2:3], off offset:2048
	v_add_co_u32_e32 v2, vcc, s62, v2
	v_mov_b32_e32 v0, v8
	s_nop 0
	v_addc_co_u32_e32 v3, vcc, 0, v3, vcc
	global_load_ushort v191, v[2:3], off
	global_load_ushort v190, v[2:3], off offset:2048
	global_load_dwordx4 v[90:93], v152, s[56:57]
	v_lshl_add_u64 v[2:3], s[56:57], 0, v[0:1]
	s_movk_i32 s63, 0x7000
	v_add_co_u32_e32 v2, vcc, s63, v2
	s_mov_b32 s75, s73
	s_nop 0
	v_addc_co_u32_e32 v3, vcc, 0, v3, vcc
	global_load_dwordx4 v[106:109], v8, s[56:57]
	global_load_dwordx4 v[94:97], v[2:3], off
	s_lshl_b64 s[56:57], s[74:75], 11
	v_lshl_add_u64 v[2:3], v[154:155], 0, s[56:57]
	s_add_i32 s56, s72, 32
	s_add_i32 s60, s60, 0x38000
	s_mov_b32 s57, s73
	s_mul_hi_u32 s59, s56, 0x1c00
	s_add_u32 s58, s36, s60
	s_addc_u32 s59, s37, s59
	s_lshl_b64 s[56:57], s[56:57], 11
	global_load_dwordx4 v[102:105], v[2:3], off
	v_lshl_add_u64 v[2:3], v[148:149], 0, s[56:57]
	global_load_ushort v247, v[148:149], off
	global_load_ushort v247, v[148:149], off
	global_load_ushort v247, v[148:149], off
	global_load_ushort v247, v[148:149], off
	global_load_dwordx4 v[118:121], v150, s[58:59]
	global_load_dwordx4 v[114:117], v150, s[58:59] offset:16
	global_load_dwordx4 v[110:113], v150, s[58:59] offset:128
	global_load_dwordx4 v[98:101], v150, s[58:59] offset:144
	global_load_ushort v189, v[2:3], off
	global_load_ushort v187, v[2:3], off offset:2048
	v_add_co_u32_e32 v2, vcc, s62, v2
	s_add_i32 s60, s74, 1
	s_nop 0
	v_addc_co_u32_e32 v3, vcc, 0, v3, vcc
	global_load_ushort v188, v[2:3], off
	global_load_ushort v186, v[2:3], off offset:2048
	global_load_dwordx4 v[58:61], v152, s[58:59]
	v_lshl_add_u64 v[2:3], s[58:59], 0, v[0:1]
	s_mov_b32 s61, s73
	v_add_co_u32_e32 v2, vcc, s63, v2
	s_lshl_b64 s[56:57], s[60:61], 11
	s_nop 0
	v_addc_co_u32_e32 v3, vcc, 0, v3, vcc
	s_min_u32 s60, s3, 2
	global_load_dwordx4 v[74:77], v8, s[58:59]
	global_load_dwordx4 v[62:65], v[2:3], off
	v_lshl_add_u64 v[2:3], v[154:155], 0, s[56:57]
	s_lshl_b32 s56, s60, 5
	s_add_i32 s56, s56, s72
	s_mul_i32 s58, s56, 0x1c00
	s_mov_b32 s57, s73
	s_mul_hi_u32 s59, s56, 0x1c00
	s_add_u32 s58, s36, s58
	s_addc_u32 s59, s37, s59
	s_lshl_b64 s[56:57], s[56:57], 11
	global_load_dwordx4 v[66:69], v[2:3], off
	v_lshl_add_u64 v[2:3], v[148:149], 0, s[56:57]
	global_load_ushort v247, v[148:149], off
	global_load_ushort v247, v[148:149], off
	global_load_ushort v247, v[148:149], off
	global_load_ushort v247, v[148:149], off
	global_load_dwordx4 v[86:89], v150, s[58:59]
	global_load_dwordx4 v[82:85], v150, s[58:59] offset:16
	global_load_dwordx4 v[78:81], v150, s[58:59] offset:128
	global_load_dwordx4 v[70:73], v150, s[58:59] offset:144
	global_load_ushort v185, v[2:3], off
	global_load_ushort v183, v[2:3], off offset:2048
	v_add_co_u32_e32 v2, vcc, s62, v2
	s_add_i32 s60, s74, s60
	s_nop 0
	v_addc_co_u32_e32 v3, vcc, 0, v3, vcc
	global_load_ushort v184, v[2:3], off
	global_load_ushort v182, v[2:3], off offset:2048
	global_load_dwordx4 v[30:33], v152, s[58:59]
	v_lshl_add_u64 v[2:3], s[58:59], 0, v[0:1]
	v_add_co_u32_e32 v2, vcc, s63, v2
	s_lshl_b64 s[56:57], s[60:61], 11
	s_nop 0
	v_addc_co_u32_e32 v3, vcc, 0, v3, vcc
	s_min_u32 s60, s3, 3
	global_load_dwordx4 v[54:57], v8, s[58:59]
	global_load_dwordx4 v[42:45], v[2:3], off
	v_lshl_add_u64 v[2:3], v[154:155], 0, s[56:57]
	s_lshl_b32 s56, s60, 5
	s_add_i32 s56, s56, s72
	s_mul_i32 s58, s56, 0x1c00
	s_mov_b32 s57, s73
	s_mul_hi_u32 s59, s56, 0x1c00
	s_add_u32 s58, s36, s58
	s_addc_u32 s59, s37, s59
	s_lshl_b64 s[56:57], s[56:57], 11
	global_load_dwordx4 v[50:53], v[2:3], off
	v_lshl_add_u64 v[2:3], v[148:149], 0, s[56:57]
	global_load_ushort v247, v[148:149], off
	global_load_ushort v247, v[148:149], off
	global_load_ushort v247, v[148:149], off
	global_load_ushort v247, v[148:149], off
	global_load_dwordx4 v[46:49], v150, s[58:59]
	global_load_dwordx4 v[38:41], v150, s[58:59] offset:16
	global_load_dwordx4 v[34:37], v150, s[58:59] offset:128
	global_load_dwordx4 v[26:29], v150, s[58:59] offset:144
	global_load_ushort v180, v[2:3], off
	global_load_ushort v178, v[2:3], off offset:2048
	v_add_co_u32_e32 v2, vcc, s62, v2
	s_add_i32 s60, s74, s60
	s_nop 0
	v_addc_co_u32_e32 v3, vcc, 0, v3, vcc
	v_lshl_add_u64 v[6:7], s[58:59], 0, v[0:1]
	v_add_co_u32_e32 v6, vcc, 0x7000, v6
	s_lshl_b64 s[56:57], s[60:61], 11
	global_load_ushort v179, v[2:3], off
	global_load_ushort v176, v[2:3], off offset:2048
	s_nop 0
	global_load_dwordx4 v[2:5], v152, s[58:59]
	v_addc_co_u32_e32 v7, vcc, 0, v7, vcc
	v_lshl_add_u64 v[14:15], v[154:155], 0, s[56:57]
	global_load_dwordx4 v[18:21], v8, s[58:59]
	s_movk_i32 s87, 0x7000
	global_load_dwordx4 v[6:9], v[6:7], off
	s_mov_b64 s[76:77], -1
	global_load_dwordx4 v[14:17], v[14:15], off
	s_and_b64 vcc, exec, s[38:39]
	v_mul_u32_u24_e32 v194, 0x110, v195
	s_cbranch_vccnz .LBB0_350
	v_mul_u32_u24_e32 v196, 0x110, v195
	s_mov_b64 s[76:77], 0
; __device__ __forceinline__ f32x4 mma_gl(const bf16x8* af, const bfr* B, int ldb, int ksteps, f32x4 acc, int fr, int fq) {
;   bf16x8 b0 = *(const bf16x8*)(B + fr * ldb + 0 * 32 + fq * 8);
;   bf16x8 b1 = *(const bf16x8*)(B + fr * ldb + 1 * 32 + fq * 8);
;   bf16x8 b2 = *(const bf16x8*)(B + fr * ldb + 2 * 32 + fq * 8);
;   bf16x8 b3 = *(const bf16x8*)(B + fr * ldb + 3 * 32 + fq * 8);
.LBB0_350:
	v_lshlrev_b32_e32 v151, 1, v151
	v_lshlrev_b32_e32 v153, 1, v153
	v_mul_u32_u24_e32 v175, 0x110, v175
	s_mov_b32 s56, 0
	s_andn2_b64 vcc, exec, s[76:77]
	v_cmp_gt_i32_e64 s[38:39], 4, v181
	v_add3_u32 v177, 0, v151, v153
	s_cbranch_vccnz .LBB0_368
	s_movk_i32 s56, 0x110
	v_mad_u32_u24 v166, v195, s56, 0
	v_lshlrev_b32_e32 v167, 2, v174
	s_movk_i32 s75, 0x1000
	v_mov_b32_e32 v151, v1
	v_mov_b32_e32 v153, v1
	v_add3_u32 v195, v166, v175, v167
	s_mov_b32 s57, 0
	s_mov_b32 s58, 7
	v_add_u32_e32 v196, v177, v175
	v_add_u32_e32 v197, s57, v141
	s_and_saveexec_b64 s[76:77], s[38:39]
	s_cbranch_execz .Lgla_dummy_e
	s_branch .LBB0_353

; #define LBAR() do { asm volatile("s_waitcnt lgkmcnt(0)" ::: "memory"); __builtin_amdgcn_s_barrier(); asm volatile("" ::: "memory"); } while (0)
; #define LBAR() do { asm volatile("s_waitcnt lgkmcnt(0)" ::: "memory"); __builtin_amdgcn_s_barrier(); asm volatile("" ::: "memory"); } while (0)
; __device__ void gla_seq(const KP& p, int l, int s, int h, int vq) {
;     ...
; #pragma unroll
;   for (int k = 0; k < 4; ++k) GLA_LOAD(k, min(k, nst - 1));
;   int st0 = 0;
;   for (; st0 + 3 < nst; st0 += 4) {
; #pragma unroll
;     for (int k = 0; k < 4; ++k) {
;       const int st = st0 + k;
;       GLA_STEP(k, st);
;       GLA_LOAD(k, min(st + 4, nst - 1));
;       LBAR();
.LBB0_353:
	ds_read_b128 v[198:201], v195
	s_add_i32 s60, s72, s57
	s_ashr_i32 s61, s60, 31
	v_cmp_gt_u32_e32 vcc, s86, v197
	s_lshl_b64 s[60:61], s[60:61], 11
	s_waitcnt vmcnt(59) lgkmcnt(0)
	v_mfma_f32_16x16x32_bf16 v[134:137], v[134:137], v[198:201], 0
	ds_read_b128 v[198:201], v195 offset:16
	s_waitcnt vmcnt(58) lgkmcnt(0)
	v_mfma_f32_16x16x32_bf16 v[130:133], v[130:133], v[198:201], 0
	ds_read_b128 v[198:201], v195 offset:128
	s_waitcnt vmcnt(57) lgkmcnt(0)
	v_mfma_f32_16x16x32_bf16 v[126:129], v[126:129], v[198:201], v[134:137]
	s_nop 2
	ds_read_b128 v[134:137], v195 offset:144
	s_waitcnt vmcnt(56) lgkmcnt(0)
	v_mfma_f32_16x16x32_bf16 v[122:125], v[122:125], v[134:137], v[130:133]
	s_nop 7
	v_pk_add_f32 v[124:125], v[128:129], v[124:125]
	v_pk_add_f32 v[122:123], v[126:127], v[122:123]
	s_waitcnt vmcnt(55)
	v_lshlrev_b32_e32 v128, 16, v193
	v_add_f32_e32 v122, v122, v128
	v_cvt_pk_bf16_f32 v122, v122, s0
	v_cndmask_b32_sdwa v122, v1, v122, vcc dst_sel:DWORD dst_unused:UNUSED_PAD src0_sel:DWORD src1_sel:WORD_0
	v_lshl_add_u64 v[126:127], v[148:149], 0, s[60:61]
	global_store_short v[126:127], v122, off
	s_waitcnt vmcnt(55)
	v_lshlrev_b32_e32 v122, 16, v192
	v_add_f32_e32 v128, v123, v122
	v_add_u32_e32 v122, 1, v197
	s_mov_b64 s[60:61], 0x800
	v_cmp_gt_u32_e32 vcc, s86, v122
	v_lshl_add_u64 v[122:123], v[126:127], 0, s[60:61]
	v_cvt_pk_bf16_f32 v128, v128, s0
	v_cndmask_b32_sdwa v128, v1, v128, vcc dst_sel:DWORD dst_unused:UNUSED_PAD src0_sel:DWORD src1_sel:WORD_0
	global_store_short v[122:123], v128, off
	s_waitcnt vmcnt(55)
	v_lshlrev_b32_e32 v122, 16, v191
	v_add_f32_e32 v124, v124, v122
	v_add_u32_e32 v122, 2, v197
	s_mov_b64 s[60:61], 0x1000
	v_cmp_gt_u32_e32 vcc, s86, v122
	v_lshl_add_u64 v[122:123], v[126:127], 0, s[60:61]
	v_cvt_pk_bf16_f32 v124, v124, s0
	v_cndmask_b32_sdwa v124, v1, v124, vcc dst_sel:DWORD dst_unused:UNUSED_PAD src0_sel:DWORD src1_sel:WORD_0
	global_store_short v[122:123], v124, off
	s_waitcnt vmcnt(55)
	v_lshlrev_b32_e32 v122, 16, v190
	v_add_f32_e32 v124, v125, v122
	v_add_u32_e32 v122, 3, v197
	v_cmp_gt_u32_e32 vcc, s86, v122
	s_mov_b64 s[60:61], 0x1800
	v_cvt_pk_bf16_f32 v124, v124, s0
	v_lshl_add_u64 v[122:123], v[126:127], 0, s[60:61]
	v_cndmask_b32_sdwa v124, v1, v124, vcc dst_sel:DWORD dst_unused:UNUSED_PAD src0_sel:DWORD src1_sel:WORD_0
	global_store_short v[122:123], v124, off
.LBB0_354:
	s_or_b64 exec, exec, s[76:77]
	s_add_i32 s56, s58, -3
	s_min_i32 s59, s56, s3
	s_lshl_b32 s60, s59, 5
	s_add_i32 s60, s60, s72
	s_ashr_i32 s61, s60, 31
	s_mul_i32 s62, s60, 0x1c00
	s_mul_hi_i32 s63, s60, 0x1c00
	s_add_u32 s62, s36, s62
	s_waitcnt vmcnt(52)
	v_pk_mul_f32 v[12:13], v[104:105], v[12:13]
	v_pk_mul_f32 v[10:11], v[102:103], v[10:11]
	v_pk_mul_f32 v[24:25], v[104:105], v[24:25]
	v_pk_mul_f32 v[22:23], v[102:103], v[22:23]
	s_addc_u32 s63, s37, s63
	v_mfma_f32_16x16x32_bf16 v[10:13], v[90:93], v[106:109], v[10:13]
	s_lshl_b64 s[60:61], s[60:61], 11
	s_add_i32 s64, s59, s74
	s_ashr_i32 s65, s64, 31
	v_mfma_f32_16x16x32_bf16 v[22:25], v[90:93], v[94:97], v[22:25]
	v_lshl_add_u64 v[90:91], s[62:63], 0, v[150:151]
	global_load_dwordx4 v[134:137], v[90:91], off
	global_load_dwordx4 v[130:133], v[90:91], off offset:16
	global_load_dwordx4 v[126:129], v[90:91], off offset:128
	global_load_dwordx4 v[122:125], v[90:91], off offset:144
	v_lshl_add_u64 v[90:91], v[148:149], 0, s[60:61]
	v_add_co_u32_e32 v92, vcc, s75, v90
	v_lshl_add_u64 v[94:95], s[62:63], 0, v[0:1]
	s_nop 0
	v_addc_co_u32_e32 v93, vcc, 0, v91, vcc
	global_load_ushort v193, v[90:91], off
	global_load_ushort v192, v[90:91], off offset:2048
	global_load_ushort v191, v[92:93], off
	global_load_ushort v190, v[92:93], off offset:2048
	v_lshl_add_u64 v[90:91], s[62:63], 0, v[152:153]
	global_load_dwordx4 v[90:93], v[90:91], off
	s_nop 0
	global_load_dwordx4 v[106:109], v[94:95], off
	v_add_co_u32_e32 v94, vcc, 0x7000, v94
	s_lshl_b64 s[60:61], s[64:65], 11
	s_nop 0
	v_addc_co_u32_e32 v95, vcc, 0, v95, vcc
	v_lshl_add_u64 v[102:103], v[154:155], 0, s[60:61]
	global_load_dwordx4 v[94:97], v[94:95], off
	v_cvt_pk_bf16_f32 v167, v12, v13
	global_load_dwordx4 v[102:105], v[102:103], off
	v_cvt_pk_bf16_f32 v166, v10, v11
	ds_write_b64 v196, v[166:167] offset:8704
	v_cvt_pk_bf16_f32 v167, v24, v25
	v_cvt_pk_bf16_f32 v166, v22, v23
	ds_write_b64 v196, v[166:167] offset:13056
	s_waitcnt lgkmcnt(0)
	s_barrier
	s_and_saveexec_b64 s[76:77], s[38:39]
	s_cbranch_execz .Lgla_dummy_a
	ds_read_b128 v[198:201], v195 offset:8704
	s_add_i32 s59, s72, s57
	s_add_i32 s60, s59, 32
	s_ashr_i32 s61, s60, 31
	s_lshl_b64 s[60:61], s[60:61], 11
	s_waitcnt vmcnt(59) lgkmcnt(0)
	v_mfma_f32_16x16x32_bf16 v[118:121], v[118:121], v[198:201], 0
	ds_read_b128 v[198:201], v195 offset:8720
	s_waitcnt vmcnt(58) lgkmcnt(0)
	v_mfma_f32_16x16x32_bf16 v[114:117], v[114:117], v[198:201], 0
	ds_read_b128 v[198:201], v195 offset:8832
	s_waitcnt vmcnt(57) lgkmcnt(0)
	v_mfma_f32_16x16x32_bf16 v[110:113], v[110:113], v[198:201], v[118:121]
	s_nop 2
	ds_read_b128 v[118:121], v195 offset:8848
	s_waitcnt vmcnt(56) lgkmcnt(0)
	v_mfma_f32_16x16x32_bf16 v[98:101], v[98:101], v[118:121], v[114:117]
	s_nop 7
	v_pk_add_f32 v[100:101], v[112:113], v[100:101]
	v_pk_add_f32 v[98:99], v[110:111], v[98:99]
	s_waitcnt vmcnt(55)
	v_lshlrev_b32_e32 v113, 16, v189
	v_add_u32_e32 v112, 32, v197
	v_add_f32_e32 v98, v98, v113
	v_cmp_gt_u32_e32 vcc, s86, v112
	v_cvt_pk_bf16_f32 v98, v98, s0
	v_lshl_add_u64 v[110:111], v[148:149], 0, s[60:61]
	v_cndmask_b32_sdwa v98, v1, v98, vcc dst_sel:DWORD dst_unused:UNUSED_PAD src0_sel:DWORD src1_sel:WORD_0
	global_store_short v[110:111], v98, off
	s_waitcnt vmcnt(55)
	v_lshlrev_b32_e32 v98, 16, v187
	v_add_f32_e32 v112, v99, v98
	v_add_u32_e32 v98, 33, v197
	s_mov_b64 s[60:61], 0x800
	v_cmp_gt_u32_e32 vcc, s86, v98
	v_lshl_add_u64 v[98:99], v[110:111], 0, s[60:61]
	v_cvt_pk_bf16_f32 v112, v112, s0
	v_cndmask_b32_sdwa v112, v1, v112, vcc dst_sel:DWORD dst_unused:UNUSED_PAD src0_sel:DWORD src1_sel:WORD_0
	global_store_short v[98:99], v112, off
	s_waitcnt vmcnt(55)
	v_lshlrev_b32_e32 v98, 16, v188
	v_add_f32_e32 v100, v100, v98
	v_add_u32_e32 v98, 34, v197
	s_mov_b64 s[60:61], 0x1000
	v_cmp_gt_u32_e32 vcc, s86, v98
	v_lshl_add_u64 v[98:99], v[110:111], 0, s[60:61]
	v_cvt_pk_bf16_f32 v100, v100, s0
	v_cndmask_b32_sdwa v100, v1, v100, vcc dst_sel:DWORD dst_unused:UNUSED_PAD src0_sel:DWORD src1_sel:WORD_0
	global_store_short v[98:99], v100, off
	s_waitcnt vmcnt(55)
	v_lshlrev_b32_e32 v98, 16, v186
	v_add_f32_e32 v100, v101, v98
	v_add_u32_e32 v98, 35, v197
	v_cmp_gt_u32_e32 vcc, s86, v98
	s_mov_b64 s[60:61], 0x1800
	v_cvt_pk_bf16_f32 v100, v100, s0
	v_lshl_add_u64 v[98:99], v[110:111], 0, s[60:61]
	v_cndmask_b32_sdwa v100, v1, v100, vcc dst_sel:DWORD dst_unused:UNUSED_PAD src0_sel:DWORD src1_sel:WORD_0
	global_store_short v[98:99], v100, off
	s_branch .LBB0_356

; #define LBAR() do { asm volatile("s_waitcnt lgkmcnt(0)" ::: "memory"); __builtin_amdgcn_s_barrier(); asm volatile("" ::: "memory"); } while (0)
; #define LBAR() do { asm volatile("s_waitcnt lgkmcnt(0)" ::: "memory"); __builtin_amdgcn_s_barrier(); asm volatile("" ::: "memory"); } while (0)
; __device__ void gla_seq(const KP& p, int l, int s, int h, int vq) {
;     ...
; #pragma unroll
;   for (int k = 0; k < 4; ++k) GLA_LOAD(k, min(k, nst - 1));
;   int st0 = 0;
;   for (; st0 + 3 < nst; st0 += 4) {
; #pragma unroll
;     for (int k = 0; k < 4; ++k) {
;       const int st = st0 + k;
;       GLA_STEP(k, st);
;       GLA_LOAD(k, min(st + 4, nst - 1));
;       LBAR();
.LBB0_356:
	s_or_b64 exec, exec, s[76:77]
	s_add_i32 s59, s58, -2
	s_min_i32 s59, s59, s3
	s_lshl_b32 s60, s59, 5
	s_add_i32 s60, s60, s72
	s_ashr_i32 s61, s60, 31
	s_mul_i32 s62, s60, 0x1c00
	s_mul_hi_i32 s63, s60, 0x1c00
	s_add_u32 s62, s36, s62
	s_waitcnt vmcnt(52)
	v_pk_mul_f32 v[12:13], v[68:69], v[12:13]
	v_pk_mul_f32 v[10:11], v[66:67], v[10:11]
	v_pk_mul_f32 v[24:25], v[68:69], v[24:25]
	v_pk_mul_f32 v[22:23], v[66:67], v[22:23]
	s_addc_u32 s63, s37, s63
	v_mfma_f32_16x16x32_bf16 v[10:13], v[58:61], v[74:77], v[10:13]
	s_lshl_b64 s[60:61], s[60:61], 11
	s_add_i32 s64, s59, s74
	s_ashr_i32 s65, s64, 31
	v_mfma_f32_16x16x32_bf16 v[22:25], v[58:61], v[62:65], v[22:25]
	v_lshl_add_u64 v[58:59], s[62:63], 0, v[150:151]
	global_load_dwordx4 v[118:121], v[58:59], off
	global_load_dwordx4 v[114:117], v[58:59], off offset:16
	global_load_dwordx4 v[110:113], v[58:59], off offset:128
	global_load_dwordx4 v[98:101], v[58:59], off offset:144
	v_lshl_add_u64 v[58:59], v[148:149], 0, s[60:61]
	v_add_co_u32_e32 v60, vcc, s75, v58
	v_lshl_add_u64 v[62:63], s[62:63], 0, v[0:1]
	s_nop 0
	v_addc_co_u32_e32 v61, vcc, 0, v59, vcc
	global_load_ushort v189, v[58:59], off
	global_load_ushort v187, v[58:59], off offset:2048
	global_load_ushort v188, v[60:61], off
	global_load_ushort v186, v[60:61], off offset:2048
	v_lshl_add_u64 v[58:59], s[62:63], 0, v[152:153]
	global_load_dwordx4 v[58:61], v[58:59], off
	s_nop 0
	global_load_dwordx4 v[74:77], v[62:63], off
	v_add_co_u32_e32 v62, vcc, 0x7000, v62
	s_lshl_b64 s[60:61], s[64:65], 11
	s_nop 0
	v_addc_co_u32_e32 v63, vcc, 0, v63, vcc
	v_lshl_add_u64 v[66:67], v[154:155], 0, s[60:61]
	global_load_dwordx4 v[62:65], v[62:63], off
	v_cvt_pk_bf16_f32 v167, v12, v13
	global_load_dwordx4 v[66:69], v[66:67], off
	v_cvt_pk_bf16_f32 v166, v10, v11
	ds_write_b64 v196, v[166:167]
	v_cvt_pk_bf16_f32 v167, v24, v25
	v_cvt_pk_bf16_f32 v166, v22, v23
	ds_write_b64 v196, v[166:167] offset:4352
	s_waitcnt lgkmcnt(0)
	s_barrier
	s_and_saveexec_b64 s[76:77], s[38:39]
	s_cbranch_execz .Lgla_dummy_b
	ds_read_b128 v[198:201], v195
	s_add_i32 s59, s72, s57
	s_add_i32 s60, s59, 64
	s_ashr_i32 s61, s60, 31
	s_lshl_b64 s[60:61], s[60:61], 11
	s_waitcnt vmcnt(59) lgkmcnt(0)
	v_mfma_f32_16x16x32_bf16 v[86:89], v[86:89], v[198:201], 0
	ds_read_b128 v[198:201], v195 offset:16
	s_waitcnt vmcnt(58) lgkmcnt(0)
	v_mfma_f32_16x16x32_bf16 v[82:85], v[82:85], v[198:201], 0
	ds_read_b128 v[198:201], v195 offset:128
	s_waitcnt vmcnt(57) lgkmcnt(0)
	v_mfma_f32_16x16x32_bf16 v[78:81], v[78:81], v[198:201], v[86:89]
	s_nop 2
	ds_read_b128 v[86:89], v195 offset:144
	s_waitcnt vmcnt(56) lgkmcnt(0)
	v_mfma_f32_16x16x32_bf16 v[70:73], v[70:73], v[86:89], v[82:85]
	s_nop 7
	v_pk_add_f32 v[72:73], v[80:81], v[72:73]
	v_pk_add_f32 v[70:71], v[78:79], v[70:71]
	s_waitcnt vmcnt(55)
	v_lshlrev_b32_e32 v81, 16, v185
	v_add_u32_e32 v80, 64, v197
	v_add_f32_e32 v70, v70, v81
	v_cmp_gt_u32_e32 vcc, s86, v80
	v_cvt_pk_bf16_f32 v70, v70, s0
	v_lshl_add_u64 v[78:79], v[148:149], 0, s[60:61]
	v_cndmask_b32_sdwa v70, v1, v70, vcc dst_sel:DWORD dst_unused:UNUSED_PAD src0_sel:DWORD src1_sel:WORD_0
	global_store_short v[78:79], v70, off
	s_waitcnt vmcnt(55)
	v_lshlrev_b32_e32 v70, 16, v183
	v_add_f32_e32 v80, v71, v70
	v_add_u32_e32 v70, 0x41, v197
	s_mov_b64 s[60:61], 0x800
	v_cmp_gt_u32_e32 vcc, s86, v70
	v_lshl_add_u64 v[70:71], v[78:79], 0, s[60:61]
	v_cvt_pk_bf16_f32 v80, v80, s0
	v_cndmask_b32_sdwa v80, v1, v80, vcc dst_sel:DWORD dst_unused:UNUSED_PAD src0_sel:DWORD src1_sel:WORD_0
	global_store_short v[70:71], v80, off
	s_waitcnt vmcnt(55)
	v_lshlrev_b32_e32 v70, 16, v184
	v_add_f32_e32 v72, v72, v70
	v_add_u32_e32 v70, 0x42, v197
	s_mov_b64 s[60:61], 0x1000
	v_cmp_gt_u32_e32 vcc, s86, v70
	v_lshl_add_u64 v[70:71], v[78:79], 0, s[60:61]
	v_cvt_pk_bf16_f32 v72, v72, s0
	v_cndmask_b32_sdwa v72, v1, v72, vcc dst_sel:DWORD dst_unused:UNUSED_PAD src0_sel:DWORD src1_sel:WORD_0
	global_store_short v[70:71], v72, off
	s_waitcnt vmcnt(55)
	v_lshlrev_b32_e32 v70, 16, v182
	v_add_f32_e32 v72, v73, v70
	v_add_u32_e32 v70, 0x43, v197
	v_cmp_gt_u32_e32 vcc, s86, v70
	s_mov_b64 s[60:61], 0x1800
	v_cvt_pk_bf16_f32 v72, v72, s0
	v_lshl_add_u64 v[70:71], v[78:79], 0, s[60:61]
	v_cndmask_b32_sdwa v72, v1, v72, vcc dst_sel:DWORD dst_unused:UNUSED_PAD src0_sel:DWORD src1_sel:WORD_0
	global_store_short v[70:71], v72, off
	s_branch .LBB0_358

; #define LBAR() do { asm volatile("s_waitcnt lgkmcnt(0)" ::: "memory"); __builtin_amdgcn_s_barrier(); asm volatile("" ::: "memory"); } while (0)
; #define LBAR() do { asm volatile("s_waitcnt lgkmcnt(0)" ::: "memory"); __builtin_amdgcn_s_barrier(); asm volatile("" ::: "memory"); } while (0)
; __device__ void gla_seq(const KP& p, int l, int s, int h, int vq) {
;     ...
; #pragma unroll
;   for (int k = 0; k < 4; ++k) GLA_LOAD(k, min(k, nst - 1));
;   int st0 = 0;
;   for (; st0 + 3 < nst; st0 += 4) {
; #pragma unroll
;     for (int k = 0; k < 4; ++k) {
;       const int st = st0 + k;
;       GLA_STEP(k, st);
;       GLA_LOAD(k, min(st + 4, nst - 1));
;       LBAR();
.LBB0_358:
	s_or_b64 exec, exec, s[76:77]
	s_add_i32 s59, s58, -1
	s_min_i32 s59, s59, s3
	s_lshl_b32 s60, s59, 5
	s_add_i32 s60, s60, s72
	s_ashr_i32 s61, s60, 31
	s_mul_i32 s62, s60, 0x1c00
	s_mul_hi_i32 s63, s60, 0x1c00
	s_add_u32 s62, s36, s62
	s_waitcnt vmcnt(52)
	v_pk_mul_f32 v[12:13], v[52:53], v[12:13]
	v_pk_mul_f32 v[10:11], v[50:51], v[10:11]
	v_pk_mul_f32 v[24:25], v[52:53], v[24:25]
	v_pk_mul_f32 v[22:23], v[50:51], v[22:23]
	s_addc_u32 s63, s37, s63
	v_mfma_f32_16x16x32_bf16 v[10:13], v[30:33], v[54:57], v[10:13]
	s_lshl_b64 s[60:61], s[60:61], 11
	s_add_i32 s64, s59, s74
	s_ashr_i32 s65, s64, 31
	v_mfma_f32_16x16x32_bf16 v[22:25], v[30:33], v[42:45], v[22:25]
	v_lshl_add_u64 v[30:31], s[62:63], 0, v[150:151]
	global_load_dwordx4 v[86:89], v[30:31], off
	global_load_dwordx4 v[82:85], v[30:31], off offset:16
	global_load_dwordx4 v[78:81], v[30:31], off offset:128
	global_load_dwordx4 v[70:73], v[30:31], off offset:144
	v_lshl_add_u64 v[30:31], v[148:149], 0, s[60:61]
	v_add_co_u32_e32 v32, vcc, s75, v30
	v_lshl_add_u64 v[42:43], s[62:63], 0, v[0:1]
	s_nop 0
	v_addc_co_u32_e32 v33, vcc, 0, v31, vcc
	global_load_ushort v185, v[30:31], off
	global_load_ushort v183, v[30:31], off offset:2048
	global_load_ushort v184, v[32:33], off
	global_load_ushort v182, v[32:33], off offset:2048
	v_lshl_add_u64 v[30:31], s[62:63], 0, v[152:153]
	global_load_dwordx4 v[30:33], v[30:31], off
	s_nop 0
	global_load_dwordx4 v[54:57], v[42:43], off
	v_add_co_u32_e32 v42, vcc, 0x7000, v42
	s_lshl_b64 s[60:61], s[64:65], 11
	s_nop 0
	v_addc_co_u32_e32 v43, vcc, 0, v43, vcc
	v_lshl_add_u64 v[50:51], v[154:155], 0, s[60:61]
	global_load_dwordx4 v[42:45], v[42:43], off
	v_cvt_pk_bf16_f32 v167, v12, v13
	global_load_dwordx4 v[50:53], v[50:51], off
	v_cvt_pk_bf16_f32 v166, v10, v11
	ds_write_b64 v196, v[166:167] offset:8704
	v_cvt_pk_bf16_f32 v167, v24, v25
	v_cvt_pk_bf16_f32 v166, v22, v23
	ds_write_b64 v196, v[166:167] offset:13056
	s_waitcnt lgkmcnt(0)
	s_barrier
	s_and_saveexec_b64 s[76:77], s[38:39]
	s_cbranch_execz .Lgla_dummy_c
	ds_read_b128 v[198:201], v195 offset:8704
	s_add_i32 s59, s72, s57
	s_add_i32 s60, s59, 0x60
	s_ashr_i32 s61, s60, 31
	s_lshl_b64 s[60:61], s[60:61], 11
	s_waitcnt vmcnt(59) lgkmcnt(0)
	v_mfma_f32_16x16x32_bf16 v[46:49], v[46:49], v[198:201], 0
	ds_read_b128 v[198:201], v195 offset:8720
	s_waitcnt vmcnt(58) lgkmcnt(0)
	v_mfma_f32_16x16x32_bf16 v[38:41], v[38:41], v[198:201], 0
	ds_read_b128 v[198:201], v195 offset:8832
	s_waitcnt vmcnt(57) lgkmcnt(0)
	v_mfma_f32_16x16x32_bf16 v[34:37], v[34:37], v[198:201], v[46:49]
	s_nop 2
	ds_read_b128 v[46:49], v195 offset:8848
	s_waitcnt vmcnt(56) lgkmcnt(0)
	v_mfma_f32_16x16x32_bf16 v[26:29], v[26:29], v[46:49], v[38:41]
	s_nop 7
	v_pk_add_f32 v[28:29], v[36:37], v[28:29]
	v_pk_add_f32 v[26:27], v[34:35], v[26:27]
	s_waitcnt vmcnt(55)
	v_lshlrev_b32_e32 v37, 16, v180
	v_add_u32_e32 v36, 0x60, v197
	v_add_f32_e32 v26, v26, v37
	v_cmp_gt_u32_e32 vcc, s86, v36
	v_cvt_pk_bf16_f32 v26, v26, s0
	v_lshl_add_u64 v[34:35], v[148:149], 0, s[60:61]
	v_cndmask_b32_sdwa v26, v1, v26, vcc dst_sel:DWORD dst_unused:UNUSED_PAD src0_sel:DWORD src1_sel:WORD_0
	global_store_short v[34:35], v26, off
	s_waitcnt vmcnt(55)
	v_lshlrev_b32_e32 v26, 16, v178
	v_add_f32_e32 v36, v27, v26
	v_add_u32_e32 v26, 0x61, v197
	s_mov_b64 s[60:61], 0x800
	v_cmp_gt_u32_e32 vcc, s86, v26
	v_lshl_add_u64 v[26:27], v[34:35], 0, s[60:61]
	v_cvt_pk_bf16_f32 v36, v36, s0
	v_cndmask_b32_sdwa v36, v1, v36, vcc dst_sel:DWORD dst_unused:UNUSED_PAD src0_sel:DWORD src1_sel:WORD_0
	global_store_short v[26:27], v36, off
	s_waitcnt vmcnt(55)
	v_lshlrev_b32_e32 v26, 16, v179
	v_add_f32_e32 v28, v28, v26
	v_add_u32_e32 v26, 0x62, v197
	s_mov_b64 s[60:61], 0x1000
	v_cmp_gt_u32_e32 vcc, s86, v26
	v_lshl_add_u64 v[26:27], v[34:35], 0, s[60:61]
	v_cvt_pk_bf16_f32 v28, v28, s0
	v_cndmask_b32_sdwa v28, v1, v28, vcc dst_sel:DWORD dst_unused:UNUSED_PAD src0_sel:DWORD src1_sel:WORD_0
	global_store_short v[26:27], v28, off
	s_waitcnt vmcnt(55)
	v_lshlrev_b32_e32 v26, 16, v176
	v_add_f32_e32 v28, v29, v26
	v_add_u32_e32 v26, 0x63, v197
	v_cmp_gt_u32_e32 vcc, s86, v26
	s_mov_b64 s[60:61], 0x1800
	v_cvt_pk_bf16_f32 v28, v28, s0
	v_lshl_add_u64 v[26:27], v[34:35], 0, s[60:61]
	v_cndmask_b32_sdwa v28, v1, v28, vcc dst_sel:DWORD dst_unused:UNUSED_PAD src0_sel:DWORD src1_sel:WORD_0
	global_store_short v[26:27], v28, off
	s_branch .LBB0_360

; #define LBAR() do { asm volatile("s_waitcnt lgkmcnt(0)" ::: "memory"); __builtin_amdgcn_s_barrier(); asm volatile("" ::: "memory"); } while (0)
; #define LBAR() do { asm volatile("s_waitcnt lgkmcnt(0)" ::: "memory"); __builtin_amdgcn_s_barrier(); asm volatile("" ::: "memory"); } while (0)
; __device__ void gla_seq(const KP& p, int l, int s, int h, int vq) {
;     ...
; #pragma unroll
;   for (int k = 0; k < 4; ++k) GLA_LOAD(k, min(k, nst - 1));
;   int st0 = 0;
;   for (; st0 + 3 < nst; st0 += 4) {
; #pragma unroll
;     for (int k = 0; k < 4; ++k) {
;       const int st = st0 + k;
;       GLA_STEP(k, st);
;       GLA_LOAD(k, min(st + 4, nst - 1));
;       LBAR();
;     }
;   }
.LBB0_360:
	s_or_b64 exec, exec, s[76:77]
	s_min_i32 s59, s58, s3
	s_lshl_b32 s60, s59, 5
	s_add_i32 s60, s60, s72
	s_ashr_i32 s61, s60, 31
	s_mul_i32 s62, s60, 0x1c00
	s_mul_hi_i32 s63, s60, 0x1c00
	s_add_u32 s62, s36, s62
	s_waitcnt vmcnt(52)
	v_pk_mul_f32 v[12:13], v[16:17], v[12:13]
	v_pk_mul_f32 v[10:11], v[14:15], v[10:11]
	v_pk_mul_f32 v[16:17], v[16:17], v[24:25]
	v_pk_mul_f32 v[14:15], v[14:15], v[22:23]
	s_addc_u32 s63, s37, s63
	v_mfma_f32_16x16x32_bf16 v[10:13], v[2:5], v[18:21], v[10:13]
	s_lshl_b64 s[60:61], s[60:61], 11
	s_add_i32 s64, s59, s74
	s_ashr_i32 s65, s64, 31
	v_mfma_f32_16x16x32_bf16 v[22:25], v[2:5], v[6:9], v[14:17]
	v_lshl_add_u64 v[2:3], s[62:63], 0, v[150:151]
	global_load_dwordx4 v[46:49], v[2:3], off
	global_load_dwordx4 v[38:41], v[2:3], off offset:16
	global_load_dwordx4 v[34:37], v[2:3], off offset:128
	global_load_dwordx4 v[26:29], v[2:3], off offset:144
	v_lshl_add_u64 v[2:3], v[148:149], 0, s[60:61]
	v_add_co_u32_e32 v4, vcc, s75, v2
	v_lshl_add_u64 v[6:7], s[62:63], 0, v[0:1]
	s_nop 0
	v_addc_co_u32_e32 v5, vcc, 0, v3, vcc
	global_load_ushort v180, v[2:3], off
	global_load_ushort v178, v[2:3], off offset:2048
	global_load_ushort v179, v[4:5], off
	global_load_ushort v176, v[4:5], off offset:2048
	v_lshl_add_u64 v[2:3], s[62:63], 0, v[152:153]
	global_load_dwordx4 v[2:5], v[2:3], off
	s_nop 0
	global_load_dwordx4 v[18:21], v[6:7], off
	v_add_co_u32_e32 v6, vcc, s87, v6
	s_lshl_b64 s[60:61], s[64:65], 11
	s_nop 0
	v_addc_co_u32_e32 v7, vcc, 0, v7, vcc
	v_lshl_add_u64 v[14:15], v[154:155], 0, s[60:61]
	global_load_dwordx4 v[6:9], v[6:7], off
	v_cvt_pk_bf16_f32 v167, v12, v13
	global_load_dwordx4 v[14:17], v[14:15], off
	v_cvt_pk_bf16_f32 v166, v10, v11
	ds_write_b64 v196, v[166:167]
	v_cvt_pk_bf16_f32 v167, v24, v25
	v_cvt_pk_bf16_f32 v166, v22, v23
	ds_write_b64 v196, v[166:167] offset:4352
	s_waitcnt lgkmcnt(0)
	s_barrier
	s_addk_i32 s57, 0x80
	s_add_i32 s59, s58, 4
	s_cmp_ge_u32 s58, s2
	s_cbranch_scc0 .LBB0_352
	s_movk_i32 s62, 0x1000
	v_cmp_gt_i32_e64 s[38:39], 4, v181
	s_cmp_lt_u32 s56, s2
	v_add3_u32 v0, 0, v194, v175
	s_cbranch_scc1 .LBB0_369

; #define LBAR() do { asm volatile("s_waitcnt lgkmcnt(0)" ::: "memory"); __builtin_amdgcn_s_barrier(); asm volatile("" ::: "memory"); } while (0)
; #define LBAR() do { asm volatile("s_waitcnt lgkmcnt(0)" ::: "memory"); __builtin_amdgcn_s_barrier(); asm volatile("" ::: "memory"); } while (0)
; __device__ void gla_seq(const KP& p, int l, int s, int h, int vq) {
;     ...
; #pragma unroll
;   for (int k = 0; k < 4; ++k) {
;     const int st = st0 + k;
;     if (st < nst) { GLA_STEP(k, st); LBAR(); }
;   }
.LBB0_363:
	s_and_saveexec_b64 s[74:75], s[38:39]
	s_cbranch_execz .LBB0_365
	s_waitcnt vmcnt(38)
	v_lshl_add_u32 v106, v174, 2, v0
	ds_read_b128 v[90:93], v106 offset:8704
	s_waitcnt vmcnt(37)
	ds_read_b128 v[94:97], v106 offset:8720
	s_waitcnt vmcnt(36)
	ds_read_b128 v[102:105], v106 offset:8832
	s_lshl_b32 s3, s3, 5
	s_add_i32 s58, s3, s72
	s_waitcnt vmcnt(35) lgkmcnt(2)
	v_mfma_f32_16x16x32_bf16 v[90:93], v[118:121], v[90:93], 0
	s_mov_b32 s59, s73
	s_lshl_b64 s[58:59], s[58:59], 11
	s_waitcnt vmcnt(33) lgkmcnt(0)
	v_mfma_f32_16x16x32_bf16 v[90:93], v[110:113], v[102:105], v[90:93]
	ds_read_b128 v[102:105], v106 offset:8848
	v_mfma_f32_16x16x32_bf16 v[94:97], v[114:117], v[94:97], 0
	s_waitcnt vmcnt(32) lgkmcnt(0)
	v_mfma_f32_16x16x32_bf16 v[94:97], v[98:101], v[102:105], v[94:97]
	s_nop 7
	v_pk_add_f32 v[92:93], v[92:93], v[96:97]
	v_pk_add_f32 v[90:91], v[90:91], v[94:95]
	s_waitcnt vmcnt(31)
	v_lshlrev_b32_e32 v97, 16, v189
	v_or_b32_e32 v96, s3, v141
	v_add_f32_e32 v90, v90, v97
	v_cmp_gt_u32_e32 vcc, s86, v96
	v_cvt_pk_bf16_f32 v90, v90, s0
	v_lshl_add_u64 v[94:95], v[148:149], 0, s[58:59]
	v_cndmask_b32_sdwa v90, v1, v90, vcc dst_sel:DWORD dst_unused:UNUSED_PAD src0_sel:DWORD src1_sel:WORD_0
	global_store_short v[94:95], v90, off
	s_waitcnt vmcnt(30)
	v_lshlrev_b32_e32 v90, 16, v187
	v_add_f32_e32 v97, v91, v90
	v_or_b32_e32 v90, 1, v96
	s_mov_b64 s[58:59], 0x800
	v_cmp_gt_u32_e32 vcc, s86, v90
	v_lshl_add_u64 v[90:91], v[94:95], 0, s[58:59]
	v_cvt_pk_bf16_f32 v97, v97, s0
	v_cndmask_b32_sdwa v97, v1, v97, vcc dst_sel:DWORD dst_unused:UNUSED_PAD src0_sel:DWORD src1_sel:WORD_0
	global_store_short v[90:91], v97, off
	s_waitcnt vmcnt(29)
	v_lshlrev_b32_e32 v90, 16, v188
	v_add_f32_e32 v92, v92, v90
	v_or_b32_e32 v90, 2, v96
	s_mov_b64 s[58:59], 0x1000
	v_cmp_gt_u32_e32 vcc, s86, v90
	v_lshl_add_u64 v[90:91], v[94:95], 0, s[58:59]
	v_cvt_pk_bf16_f32 v92, v92, s0
	v_cndmask_b32_sdwa v92, v1, v92, vcc dst_sel:DWORD dst_unused:UNUSED_PAD src0_sel:DWORD src1_sel:WORD_0
	global_store_short v[90:91], v92, off
	s_waitcnt vmcnt(28)
	v_lshlrev_b32_e32 v90, 16, v186
	v_add_f32_e32 v92, v93, v90
	v_or_b32_e32 v90, 3, v96
	v_cmp_gt_u32_e32 vcc, s86, v90
	s_mov_b64 s[58:59], 0x1800
	v_cvt_pk_bf16_f32 v92, v92, s0
	v_lshl_add_u64 v[90:91], v[94:95], 0, s[58:59]
	v_cndmask_b32_sdwa v92, v1, v92, vcc dst_sel:DWORD dst_unused:UNUSED_PAD src0_sel:DWORD src1_sel:WORD_0
	global_store_short v[90:91], v92, off

; #define LBAR() do { asm volatile("s_waitcnt lgkmcnt(0)" ::: "memory"); __builtin_amdgcn_s_barrier(); asm volatile("" ::: "memory"); } while (0)
; #define LBAR() do { asm volatile("s_waitcnt lgkmcnt(0)" ::: "memory"); __builtin_amdgcn_s_barrier(); asm volatile("" ::: "memory"); } while (0)
; __device__ void gla_seq(const KP& p, int l, int s, int h, int vq) {
;     ...
; #pragma unroll
;   for (int k = 0; k < 4; ++k) {
;     const int st = st0 + k;
;     if (st < nst) { GLA_STEP(k, st); LBAR(); }
;   }
.LBB0_369:
	s_and_saveexec_b64 s[74:75], s[38:39]
	s_cbranch_execz .LBB0_371
	v_lshl_add_u32 v154, v174, 2, v0
	ds_read_b128 v[150:153], v154
	s_lshl_b32 s3, s56, 5
	s_add_i32 s58, s3, s72
	s_mov_b32 s59, s73
	s_lshl_b64 s[58:59], s[58:59], 11
	s_waitcnt vmcnt(47) lgkmcnt(0)
	v_mfma_f32_16x16x32_bf16 v[134:137], v[134:137], v[150:153], 0
	ds_read_b128 v[150:153], v154 offset:16
	s_waitcnt vmcnt(46) lgkmcnt(0)
	v_mfma_f32_16x16x32_bf16 v[130:133], v[130:133], v[150:153], 0
	ds_read_b128 v[150:153], v154 offset:128
	s_waitcnt vmcnt(45) lgkmcnt(0)
	v_mfma_f32_16x16x32_bf16 v[126:129], v[126:129], v[150:153], v[134:137]
	s_nop 2
	ds_read_b128 v[134:137], v154 offset:144
	s_waitcnt vmcnt(44) lgkmcnt(0)
	v_mfma_f32_16x16x32_bf16 v[122:125], v[122:125], v[134:137], v[130:133]
	s_nop 7
	v_pk_add_f32 v[124:125], v[128:129], v[124:125]
	v_pk_add_f32 v[122:123], v[126:127], v[122:123]
	s_waitcnt vmcnt(43)
	v_lshlrev_b32_e32 v129, 16, v193
	v_or_b32_e32 v128, s3, v141
	v_add_f32_e32 v122, v122, v129
	v_cmp_gt_u32_e32 vcc, s86, v128
	v_cvt_pk_bf16_f32 v122, v122, s0
	v_lshl_add_u64 v[126:127], v[148:149], 0, s[58:59]
	v_cndmask_b32_sdwa v122, v1, v122, vcc dst_sel:DWORD dst_unused:UNUSED_PAD src0_sel:DWORD src1_sel:WORD_0
	global_store_short v[126:127], v122, off
	s_waitcnt vmcnt(42)
	v_lshlrev_b32_e32 v122, 16, v192
	v_add_f32_e32 v129, v123, v122
	v_or_b32_e32 v122, 1, v128
	s_mov_b64 s[58:59], 0x800
	v_cmp_gt_u32_e32 vcc, s86, v122
	v_lshl_add_u64 v[122:123], v[126:127], 0, s[58:59]
	v_cvt_pk_bf16_f32 v129, v129, s0
	v_cndmask_b32_sdwa v129, v1, v129, vcc dst_sel:DWORD dst_unused:UNUSED_PAD src0_sel:DWORD src1_sel:WORD_0
	global_store_short v[122:123], v129, off
	s_waitcnt vmcnt(41)
	v_lshlrev_b32_e32 v122, 16, v191
	v_add_f32_e32 v124, v124, v122
	v_or_b32_e32 v122, 2, v128
	s_mov_b64 s[58:59], 0x1000
	v_cmp_gt_u32_e32 vcc, s86, v122
	v_lshl_add_u64 v[122:123], v[126:127], 0, s[58:59]
	v_cvt_pk_bf16_f32 v124, v124, s0
	v_cndmask_b32_sdwa v124, v1, v124, vcc dst_sel:DWORD dst_unused:UNUSED_PAD src0_sel:DWORD src1_sel:WORD_0
	global_store_short v[122:123], v124, off
	s_waitcnt vmcnt(40)
	v_lshlrev_b32_e32 v122, 16, v190
	v_add_f32_e32 v124, v125, v122
	v_or_b32_e32 v122, 3, v128
	v_cmp_gt_u32_e32 vcc, s86, v122
	s_mov_b64 s[58:59], 0x1800
	v_cvt_pk_bf16_f32 v124, v124, s0
	v_lshl_add_u64 v[122:123], v[126:127], 0, s[58:59]
	v_cndmask_b32_sdwa v124, v1, v124, vcc dst_sel:DWORD dst_unused:UNUSED_PAD src0_sel:DWORD src1_sel:WORD_0
	global_store_short v[122:123], v124, off

; #define LBAR() do { asm volatile("s_waitcnt lgkmcnt(0)" ::: "memory"); __builtin_amdgcn_s_barrier(); asm volatile("" ::: "memory"); } while (0)
; #define LBAR() do { asm volatile("s_waitcnt lgkmcnt(0)" ::: "memory"); __builtin_amdgcn_s_barrier(); asm volatile("" ::: "memory"); } while (0)
; __device__ void gla_seq(const KP& p, int l, int s, int h, int vq) {
;     ...
; #pragma unroll
;   for (int k = 0; k < 4; ++k) {
;     const int st = st0 + k;
;     if (st < nst) { GLA_STEP(k, st); LBAR(); }
;   }
.LBB0_373:
	s_and_saveexec_b64 s[74:75], s[38:39]
	s_cbranch_execz .LBB0_375
	s_waitcnt vmcnt(26)
	v_lshl_add_u32 v74, v174, 2, v0
	ds_read_b128 v[58:61], v74
	s_waitcnt vmcnt(25)
	ds_read_b128 v[62:65], v74 offset:16
	s_waitcnt vmcnt(24)
	ds_read_b128 v[66:69], v74 offset:128
	s_lshl_b32 s3, s3, 5
	s_add_i32 s58, s3, s72
	s_waitcnt vmcnt(23) lgkmcnt(2)
	v_mfma_f32_16x16x32_bf16 v[58:61], v[86:89], v[58:61], 0
	s_mov_b32 s59, s73
	s_lshl_b64 s[58:59], s[58:59], 11
	s_waitcnt vmcnt(21) lgkmcnt(0)
	v_mfma_f32_16x16x32_bf16 v[58:61], v[78:81], v[66:69], v[58:61]
	ds_read_b128 v[66:69], v74 offset:144
	v_mfma_f32_16x16x32_bf16 v[62:65], v[82:85], v[62:65], 0
	s_waitcnt vmcnt(20) lgkmcnt(0)
	v_mfma_f32_16x16x32_bf16 v[62:65], v[70:73], v[66:69], v[62:65]
	s_nop 7
	v_pk_add_f32 v[60:61], v[60:61], v[64:65]
	v_pk_add_f32 v[58:59], v[58:59], v[62:63]
	s_waitcnt vmcnt(19)
	v_lshlrev_b32_e32 v65, 16, v185
	v_or_b32_e32 v64, s3, v141
	v_add_f32_e32 v58, v58, v65
	v_cmp_gt_u32_e32 vcc, s86, v64
	v_cvt_pk_bf16_f32 v58, v58, s0
	v_lshl_add_u64 v[62:63], v[148:149], 0, s[58:59]
	v_cndmask_b32_sdwa v58, v1, v58, vcc dst_sel:DWORD dst_unused:UNUSED_PAD src0_sel:DWORD src1_sel:WORD_0
	global_store_short v[62:63], v58, off
	s_waitcnt vmcnt(18)
	v_lshlrev_b32_e32 v58, 16, v183
	v_add_f32_e32 v65, v59, v58
	v_or_b32_e32 v58, 1, v64
	s_mov_b64 s[58:59], 0x800
	v_cmp_gt_u32_e32 vcc, s86, v58
	v_lshl_add_u64 v[58:59], v[62:63], 0, s[58:59]
	v_cvt_pk_bf16_f32 v65, v65, s0
	v_cndmask_b32_sdwa v65, v1, v65, vcc dst_sel:DWORD dst_unused:UNUSED_PAD src0_sel:DWORD src1_sel:WORD_0
	global_store_short v[58:59], v65, off
	s_waitcnt vmcnt(17)
	v_lshlrev_b32_e32 v58, 16, v184
	v_add_f32_e32 v60, v60, v58
	v_or_b32_e32 v58, 2, v64
	s_mov_b64 s[58:59], 0x1000
	v_cmp_gt_u32_e32 vcc, s86, v58
	v_lshl_add_u64 v[58:59], v[62:63], 0, s[58:59]
	v_cvt_pk_bf16_f32 v60, v60, s0
	v_cndmask_b32_sdwa v60, v1, v60, vcc dst_sel:DWORD dst_unused:UNUSED_PAD src0_sel:DWORD src1_sel:WORD_0
	global_store_short v[58:59], v60, off
	s_waitcnt vmcnt(16)
	v_lshlrev_b32_e32 v58, 16, v182
	v_add_f32_e32 v60, v61, v58
	v_or_b32_e32 v58, 3, v64
	v_cmp_gt_u32_e32 vcc, s86, v58
	s_mov_b64 s[58:59], 0x1800
	v_cvt_pk_bf16_f32 v60, v60, s0
	v_lshl_add_u64 v[58:59], v[62:63], 0, s[58:59]
	v_cndmask_b32_sdwa v60, v1, v60, vcc dst_sel:DWORD dst_unused:UNUSED_PAD src0_sel:DWORD src1_sel:WORD_0
	global_store_short v[58:59], v60, off

; #define LBAR() do { asm volatile("s_waitcnt lgkmcnt(0)" ::: "memory"); __builtin_amdgcn_s_barrier(); asm volatile("" ::: "memory"); } while (0)
; #define LBAR() do { asm volatile("s_waitcnt lgkmcnt(0)" ::: "memory"); __builtin_amdgcn_s_barrier(); asm volatile("" ::: "memory"); } while (0)
; __device__ void gla_seq(const KP& p, int l, int s, int h, int vq) {
;     ...
; #pragma unroll
;   for (int k = 0; k < 4; ++k) {
;     const int st = st0 + k;
;     if (st < nst) { GLA_STEP(k, st); LBAR(); }
;   }
.LBB0_377:
	s_and_saveexec_b64 s[74:75], s[38:39]
	s_cbranch_execz .LBB0_379
	v_lshl_add_u32 v0, v174, 2, v0
	s_waitcnt vmcnt(15)
	ds_read_b128 v[30:33], v0 offset:8704
	s_waitcnt vmcnt(13)
	ds_read_b128 v[42:45], v0 offset:8720
	s_lshl_b32 s2, s3, 5
	s_add_i32 s72, s2, s72
	s_waitcnt vmcnt(10) lgkmcnt(0)
	v_mfma_f32_16x16x32_bf16 v[38:41], v[38:41], v[42:45], 0
	ds_read_b128 v[42:45], v0 offset:8832
	v_mfma_f32_16x16x32_bf16 v[30:33], v[46:49], v[30:33], 0
	s_waitcnt vmcnt(9) lgkmcnt(0)
	v_mfma_f32_16x16x32_bf16 v[30:33], v[34:37], v[42:45], v[30:33]
	ds_read_b128 v[34:37], v0 offset:8848
	v_or_b32_e32 v0, s2, v141
	v_cmp_gt_u32_e32 vcc, s86, v0
	s_waitcnt vmcnt(8) lgkmcnt(0)
	v_mfma_f32_16x16x32_bf16 v[26:29], v[26:29], v[34:37], v[38:41]
	s_lshl_b64 s[2:3], s[72:73], 11
	s_nop 6
	v_pk_add_f32 v[28:29], v[32:33], v[28:29]
	v_pk_add_f32 v[26:27], v[30:31], v[26:27]
	s_waitcnt vmcnt(7)
	v_lshlrev_b32_e32 v32, 16, v180
	v_add_f32_e32 v26, v26, v32
	v_cvt_pk_bf16_f32 v26, v26, s0
	v_cndmask_b32_sdwa v26, v1, v26, vcc dst_sel:DWORD dst_unused:UNUSED_PAD src0_sel:DWORD src1_sel:WORD_0
	v_lshl_add_u64 v[30:31], v[148:149], 0, s[2:3]
	global_store_short v[30:31], v26, off
	s_waitcnt vmcnt(6)
	v_lshlrev_b32_e32 v26, 16, v178
	v_add_f32_e32 v32, v27, v26
	v_or_b32_e32 v26, 1, v0
	s_mov_b64 s[2:3], 0x800
	v_cmp_gt_u32_e32 vcc, s86, v26
	v_lshl_add_u64 v[26:27], v[30:31], 0, s[2:3]
	v_cvt_pk_bf16_f32 v32, v32, s0
	v_cndmask_b32_sdwa v32, v1, v32, vcc dst_sel:DWORD dst_unused:UNUSED_PAD src0_sel:DWORD src1_sel:WORD_0
	global_store_short v[26:27], v32, off
	s_waitcnt vmcnt(5)
	v_lshlrev_b32_e32 v26, 16, v179
	v_add_f32_e32 v28, v28, v26
	v_or_b32_e32 v26, 2, v0
	s_mov_b64 s[2:3], 0x1000
	v_cmp_gt_u32_e32 vcc, s86, v26
	v_lshl_add_u64 v[26:27], v[30:31], 0, s[2:3]
	v_cvt_pk_bf16_f32 v28, v28, s0
	v_cndmask_b32_sdwa v28, v1, v28, vcc dst_sel:DWORD dst_unused:UNUSED_PAD src0_sel:DWORD src1_sel:WORD_0
	global_store_short v[26:27], v28, off
	s_waitcnt vmcnt(4)
	v_lshlrev_b32_e32 v26, 16, v176
	v_add_f32_e32 v28, v29, v26
	v_or_b32_e32 v0, 3, v0
	v_cmp_gt_u32_e32 vcc, s86, v0
	s_mov_b64 s[2:3], 0x1800
	v_cvt_pk_bf16_f32 v0, v28, s0
	v_lshl_add_u64 v[26:27], v[30:31], 0, s[2:3]
	v_cndmask_b32_sdwa v0, v1, v0, vcc dst_sel:DWORD dst_unused:UNUSED_PAD src0_sel:DWORD src1_sel:WORD_0
	global_store_short v[26:27], v0, off

; __device__ void ssd_seq(const KP& p, int l, int s, int h, int ph) {
;     ...
;   const unsigned coff = (unsigned)(((ti * 16 + fr) * NIN + 1280 + g * 128 + fq * 8) * 2);
;   unsigned xoff[2];
; #pragma unroll
;   for (int pt = 0; pt < 2; ++pt) xoff[pt] = (unsigned)(((ph * 32 + pt * 16 + fr) * NIN + 512 + h * 64 + fq * 8) * 2);
;   const unsigned boff = (unsigned)((((nB >> 1)) * NIN + 1024 + g * 128 + (nB & 1) * 64 + fq * 8) * 2);
;   const unsigned zoff = (unsigned)(((ti * 16 + fq * 4) * NIN + zc) * 2);
;   const unsigned yoff = (unsigned)(((ti * 16 + fq * 4) * DM + zc) * 2);
;   const unsigned cuoff = (unsigned)(((ti * 16 + fq * 4) * 8 + h) * 4);
;     ...
; #pragma unroll
;   for (int k = 0; k < 2; ++k) SSD_LOAD(k, row0 + min(k, nch - 1) * 64);
.LBB0_402:
	s_lshl_b32 s0, s3, 6
	v_and_b32_e32 v107, 15, v0
	s_waitcnt vmcnt(0)
	v_cvt_pk_bf16_f32 v4, v49, s0
	v_ashrrev_i32_e32 v144, 3, v0
	ds_write_b16 v3, v4 offset:4896
	v_and_b32_e32 v124, -16, v144
	s_movk_i32 s15, 0xe00
	v_or_b32_e32 v4, s85, v107
	v_lshrrev_b32_e32 v2, 1, v2
	v_or_b32_e32 v3, v124, v107
	s_lshl_b32 s14, s3, 5
	v_lshlrev_b32_e32 v51, 3, v104
	v_mul_u32_u24_e32 v4, 0xe00, v4
	v_mul_lo_u32 v2, v2, s15
	v_lshlrev_b32_e32 v0, 6, v0
	s_or_b32 s1, s0, s85
	v_and_b32_e32 v105, 16, v50
	v_mul_lo_u32 v3, v3, s15
	s_and_b32 s14, s14, 0x80
	v_or3_b32 v4, v4, v51, s0
	v_mov_b32_e32 v5, 0x400
	v_and_or_b32 v0, v0, 64, v2
	v_or3_b32 v3, v3, s14, v51
	v_lshl_add_u32 v92, v4, 1, v5
	v_or3_b32 v4, s1, v107, v105
	v_or3_b32 v0, v0, s14, v51
	s_lshl_b32 s14, s3, 2
	s_mul_i32 s1, s92, 0x1c00
	v_or_b32_e32 v111, v91, v124
	s_mul_hi_u32 s0, s92, 0x1c00
	s_add_u32 s56, s36, s1
	v_lshl_add_u32 v96, v0, 1, v171
	v_mul_lo_u32 v0, v111, s15
	s_addc_u32 s57, s37, s0
	v_mov_b32_e32 v93, v1
	v_lshl_add_u32 v94, v3, 1, v170
	v_lshl_add_u32 v92, v51, 1, v92
	v_lshl_add_u32 v94, v51, 1, v94
	v_lshl_add_u32 v96, v51, 1, v96
	v_or_b32_e32 v0, v0, v4
	v_lshl_add_u64 v[2:3], s[56:57], 0, v[92:93]
	s_mov_b64 s[60:61], 0x1c000
	v_lshlrev_b32_e32 v98, 1, v0
	v_lshlrev_b32_e32 v0, 1, v4
	v_mov_b32_e32 v99, v1
	v_lshl_add_u64 v[4:5], v[2:3], 0, s[60:61]
	v_add_co_u32_e32 v2, vcc, s94, v2
	v_lshl_or_b32 v0, v111, 11, v0
	s_mov_b32 s93, s73
	v_addc_co_u32_e32 v3, vcc, 0, v3, vcc
	v_lshl_add_u64 v[54:55], s[56:57], 0, v[98:99]
	v_lshl_add_u64 v[102:103], s[42:43], 0, v[0:1]
	s_lshl_b64 s[0:1], s[92:93], 11
	v_add_co_u32_e32 v56, vcc, s62, v54
	v_lshl_add_u64 v[52:53], v[102:103], 0, s[0:1]
	s_nop 0
	v_addc_co_u32_e32 v57, vcc, 0, v55, vcc
	v_add_co_u32_e32 v58, vcc, s62, v52
	s_movk_i32 s60, 0x3000
	s_nop 0
	v_addc_co_u32_e32 v59, vcc, 0, v53, vcc
	v_add_co_u32_e32 v60, vcc, s60, v54
	s_lshl_b64 s[58:59], s[92:93], 5
	s_nop 0
	v_addc_co_u32_e32 v61, vcc, 0, v55, vcc
	s_add_u32 s58, s78, s58
	v_add_co_u32_e32 v54, vcc, 0x5000, v54
	s_waitcnt lgkmcnt(0)
	s_barrier
	v_mov_b32_e32 v62, s14
	v_lshl_or_b32 v100, v111, 5, s14
	global_load_dwordx4 v[34:37], v94, s[56:57] offset:16
	global_load_dwordx4 v[30:33], v94, s[56:57] offset:128
	global_load_dwordx4 v[26:29], v94, s[56:57] offset:144
	global_load_dwordx4 v[22:25], v92, s[56:57]
	global_load_dwordx4 v[18:21], v92, s[56:57] offset:16
	global_load_dwordx4 v[6:9], v[2:3], off
	s_nop 0
	global_load_dwordx4 v[2:5], v[4:5], off offset:16
	s_nop 0
	global_load_dwordx4 v[38:41], v94, s[56:57]
	global_load_dwordx4 v[10:13], v96, s[56:57] offset:16
	s_addc_u32 s59, s79, s59
	global_load_dwordx4 v[14:17], v96, s[56:57]
	global_load_ushort v128, v98, s[56:57]
	v_addc_co_u32_e32 v55, vcc, 0, v55, vcc
	global_load_ushort v129, v[52:53], off
	global_load_ushort v125, v[52:53], off offset:2048
	global_load_ushort v126, v[56:57], off offset:3072
	global_load_ushort v119, v[58:59], off
	global_load_ushort v120, v[60:61], off offset:2048
	global_load_ushort v117, v[54:55], off offset:1024
	global_load_ushort v116, v[58:59], off offset:2048
	global_load_dword v130, v100, s[58:59]
	global_load_dword v127, v100, s[58:59] offset:32
	global_load_dword v123, v100, s[58:59] offset:64
	global_load_dword v118, v100, s[58:59] offset:96
	global_load_dword v112, v62, s[58:59] offset:2016
	v_and_b32_e32 v90, -16, v50
	s_movk_i32 s15, 0x110
	v_mul_u32_u24_e32 v108, 0x440, v104
	s_mov_b32 s3, 0
	s_andn2_b64 vcc, exec, s[38:39]
	v_mul_u32_u24_e32 v113, 0x110, v107
	v_lshlrev_b32_e32 v109, 1, v90
	v_lshlrev_b32_e32 v110, 1, v107
	v_lshlrev_b32_e32 v114, 2, v51
	v_mad_u32_u24 v115, v105, s15, 0
	s_cbranch_vccnz .LBB0_406
	s_add_i32 s15, s87, -1
	s_add_i32 s72, s15, s92
	s_and_b32 s58, s2, 0x1c0
	s_and_b32 s59, s82, 32
	s_lshl_b64 s[2:3], s[72:73], 5
	s_add_u32 s2, s78, s2
	s_addc_u32 s3, s79, s3
	v_mov_b32_e32 v101, v1
	s_add_u32 s56, s2, s14
	s_addc_u32 s57, s3, 0
	v_lshl_add_u64 v[50:51], s[2:3], 0, v[100:101]
	s_mul_i32 s2, s72, 0x1c00
	s_mul_hi_u32 s3, s72, 0x1c00
	s_add_u32 s2, s36, s2
	s_addc_u32 s3, s37, s3
	v_lshl_add_u64 v[52:53], s[2:3], 0, v[98:99]
	s_movk_i32 s61, 0x5000
	global_load_dword v143, v1, s[56:57] offset:2016
	v_add_co_u32_e32 v54, vcc, s61, v52
	s_lshl_b64 s[56:57], s[72:73], 11
	s_nop 0
	v_addc_co_u32_e32 v55, vcc, 0, v53, vcc
	v_lshl_add_u64 v[56:57], v[102:103], 0, s[56:57]
	v_add_co_u32_e32 v58, vcc, s62, v56
	v_mov_b32_e32 v95, v1
	s_nop 0
	v_addc_co_u32_e32 v59, vcc, 0, v57, vcc
	v_add_co_u32_e32 v60, vcc, s60, v52
	v_mov_b32_e32 v97, v1
	s_nop 0
	v_addc_co_u32_e32 v61, vcc, 0, v53, vcc
	v_add_co_u32_e32 v62, vcc, s62, v52
	v_add_u32_e32 v64, 0x1c000, v92
	s_nop 0
	v_addc_co_u32_e32 v63, vcc, 0, v53, vcc
	global_load_dword v142, v[50:51], off offset:96
	global_load_dword v135, v[50:51], off offset:64
	global_load_dword v137, v[50:51], off offset:32
	global_load_dword v139, v[50:51], off
	global_load_ushort v141, v[54:55], off offset:1024
	global_load_ushort v131, v[58:59], off offset:2048
	global_load_ushort v132, v[60:61], off offset:2048
	global_load_ushort v136, v[62:63], off offset:3072
	global_load_ushort v133, v[58:59], off
	global_load_ushort v134, v[56:57], off offset:2048
	global_load_ushort v140, v[56:57], off
	global_load_ushort v138, v[52:53], off
	v_lshl_add_u64 v[50:51], s[2:3], 0, v[96:97]
	v_lshl_add_u64 v[62:63], s[2:3], 0, v[92:93]
	v_lshl_add_u64 v[86:87], s[2:3], 0, v[94:95]
	global_load_dwordx4 v[66:69], v[50:51], off offset:16
	global_load_dwordx4 v[70:73], v[50:51], off
	s_nop 0
	global_load_dwordx4 v[50:53], v64, s[2:3] offset:16
	global_load_dwordx4 v[54:57], v64, s[2:3]
	global_load_dwordx4 v[58:61], v[62:63], off offset:16
	s_nop 0
	global_load_dwordx4 v[62:65], v[62:63], off
	s_nop 0
	global_load_dwordx4 v[74:77], v[86:87], off offset:144
	global_load_dwordx4 v[78:81], v[86:87], off offset:128
	global_load_dwordx4 v[82:85], v[86:87], off offset:16
	s_nop 0
	global_load_dwordx4 v[86:89], v[86:87], off
	s_movk_i32 s2, 0x43
	v_add3_u32 v124, v124, v91, s2
	s_or_b32 s2, s58, s59
	v_lshlrev_b32_e32 v144, 11, v144
	v_or_b32_e32 v105, s2, v105
	v_and_b32_e32 v144, 0xffff8000, v144
	v_lshlrev_b32_e32 v104, 13, v104
	v_add_lshl_u32 v105, v105, v107, 1
	s_add_u32 s0, s91, s0
	v_or3_b32 v104, v144, v104, v105
	v_mov_b32_e32 v105, v1
	s_addc_u32 s1, s90, s1
	v_add3_u32 v121, 0, v109, v110
	v_add3_u32 v122, v115, v113, v114
	v_lshl_add_u64 v[104:105], s[0:1], 0, v[104:105]
	s_mov_b32 s0, 3
	s_mov_b64 s[58:59], 0x800
	s_mov_b64 s[64:65], 0x1000
	s_mov_b64 s[80:81], 0x1800
	s_mov_b64 s[70:71], 0x1c000
; #define LBAR() do { asm volatile("s_waitcnt lgkmcnt(0)" ::: "memory"); __builtin_amdgcn_s_barrier(); asm volatile("" ::: "memory"); } while (0)
; #define LBAR() do { asm volatile("s_waitcnt lgkmcnt(0)" ::: "memory"); __builtin_amdgcn_s_barrier(); asm volatile("" ::: "memory"); } while (0)
; __device__ void ssd_seq(const KP& p, int l, int s, int h, int ph) {
;     ...
; #pragma unroll
;   for (int k = 0; k < 2; ++k) SSD_LOAD(k, row0 + min(k, nch - 1) * 64);
;   int c0 = 0;
;   for (; c0 + 1 < nch; c0 += 2) {
; #pragma unroll
;     for (int k = 0; k < 2; ++k) {
;       const int c = c0 + k;
;       SSD_STEP(k, c);
;       SSD_LOAD(k, row0 + min(c + 2, nch - 1) * 64);
;       LBAR();
.LBB0_404:
	ds_read_b128 v[144:147], v122
	ds_read_b128 v[148:151], v122 offset:16
	ds_read_b128 v[152:155], v122 offset:128
	ds_read_b128 v[174:177], v122 offset:144
	s_mov_b32 s76, s0
	s_waitcnt vmcnt(38) lgkmcnt(3)
	v_mfma_f32_16x16x32_bf16 v[38:41], v[38:41], v[144:147], 0
	s_mov_b32 s0, 0xfffe0000
	s_mov_b32 s1, -1
	v_add_u32_e32 v145, v121, v108
	s_waitcnt lgkmcnt(2)
	v_mfma_f32_16x16x32_bf16 v[34:37], v[34:37], v[148:151], 0
	v_add_u32_e32 v144, v121, v106
	s_waitcnt lgkmcnt(1)
	v_mfma_f32_16x16x32_bf16 v[30:33], v[30:33], v[152:155], v[38:41]
	s_waitcnt lgkmcnt(0)
	v_mfma_f32_16x16x32_bf16 v[26:29], v[26:29], v[174:177], v[34:37]
	s_waitcnt vmcnt(27)
	s_nop 1
	v_mul_f32_e32 v34, 0x3fb8aa3b, v130
	v_exp_f32_e32 v34, v34
	s_nop 2
	v_pk_add_f32 v[28:29], v[32:33], v[28:29]
	v_pk_add_f32 v[26:27], v[30:31], v[26:27]
	v_lshlrev_b32_e32 v33, 16, v129
	v_fmac_f32_e32 v33, v34, v26
	v_lshlrev_b32_e32 v26, 16, v128
	v_mul_f32_e32 v34, 0xbfb8aa3b, v26
	v_exp_f32_e32 v34, v34
	v_add_u32_e32 v32, 0xffffffbd, v124
	v_lshl_add_u64 v[30:31], v[104:105], 0, s[0:1]
	v_cmp_gt_i32_e32 vcc, s86, v32
	v_add_f32_e32 v34, 1.0, v34
	v_rcp_f32_e32 v34, v34
	s_nop 0
	v_mul_f32_e32 v26, v34, v26
	v_mul_f32_e32 v26, v26, v33
	v_cvt_pk_bf16_f32 v26, v26, s0
	v_and_b32_e32 v26, 0xffff, v26
	v_cndmask_b32_e32 v26, 0, v26, vcc
	global_store_short v[30:31], v26, off
	s_waitcnt vmcnt(26)
	v_mul_f32_e32 v30, 0x3fb8aa3b, v127
	v_exp_f32_e32 v30, v30
	v_lshlrev_b32_e32 v26, 16, v125
	s_mov_b32 s0, 0xfffe0800
	s_mov_b32 s1, -1
	v_fmac_f32_e32 v26, v30, v27
	v_lshlrev_b32_e32 v27, 16, v126
	v_mul_f32_e32 v30, 0xbfb8aa3b, v27
	v_exp_f32_e32 v30, v30
	s_nop 0
	v_add_f32_e32 v30, 1.0, v30
	v_rcp_f32_e32 v30, v30
	s_nop 0
	v_mul_f32_e32 v27, v30, v27
	v_mul_f32_e32 v30, v27, v26
	v_add_u32_e32 v26, 0xffffffbe, v124
	v_cvt_pk_bf16_f32 v30, v30, s0
	v_cmp_gt_i32_e32 vcc, s86, v26
	v_lshl_add_u64 v[26:27], v[104:105], 0, s[0:1]
	v_and_b32_e32 v30, 0xffff, v30
	v_cndmask_b32_e32 v30, 0, v30, vcc
	global_store_short v[26:27], v30, off
	s_waitcnt vmcnt(25)
	v_mul_f32_e32 v27, 0x3fb8aa3b, v123
	v_exp_f32_e32 v27, v27
	v_lshlrev_b32_e32 v26, 16, v119
	s_mov_b32 s0, 0xfffe1000
	s_mov_b32 s1, -1
	v_fmac_f32_e32 v26, v27, v28
	v_lshlrev_b32_e32 v27, 16, v120
	v_mul_f32_e32 v28, 0xbfb8aa3b, v27
	v_exp_f32_e32 v28, v28
	s_nop 0
	v_add_f32_e32 v28, 1.0, v28
	v_rcp_f32_e32 v28, v28
	s_nop 0
	v_mul_f32_e32 v27, v28, v27
	v_mul_f32_e32 v28, v27, v26
	v_add_u32_e32 v26, 0xffffffbf, v124
	v_cvt_pk_bf16_f32 v28, v28, s0
	v_cmp_gt_i32_e32 vcc, s86, v26
	v_lshl_add_u64 v[26:27], v[104:105], 0, s[0:1]
	v_and_b32_e32 v28, 0xffff, v28
	v_cndmask_b32_e32 v28, 0, v28, vcc
	global_store_short v[26:27], v28, off
	s_waitcnt vmcnt(24)
	v_mul_f32_e32 v27, 0x3fb8aa3b, v118
	v_exp_f32_e32 v27, v27
	v_lshlrev_b32_e32 v26, 16, v116
	s_mov_b32 s0, 0xfffe1800
	s_mov_b32 s1, -1
	v_fmac_f32_e32 v26, v27, v29
	v_lshlrev_b32_e32 v27, 16, v117
	v_mul_f32_e32 v28, 0xbfb8aa3b, v27
	v_exp_f32_e32 v28, v28
	s_nop 0
	v_add_f32_e32 v28, 1.0, v28
	v_rcp_f32_e32 v28, v28
	s_nop 0
	v_mul_f32_e32 v27, v28, v27
	v_mul_f32_e32 v28, v27, v26
	v_subrev_u32_e32 v26, 64, v124
	v_cvt_pk_bf16_f32 v28, v28, s0
	v_cmp_gt_i32_e32 vcc, s86, v26
	v_lshl_add_u64 v[26:27], v[104:105], 0, s[0:1]
	v_and_b32_e32 v28, 0xffff, v28
	v_cndmask_b32_e32 v28, 0, v28, vcc
	global_store_short v[26:27], v28, off
	s_waitcnt vmcnt(23)
	v_mul_f32_e32 v26, 0x3fb8aa3b, v112
	v_exp_f32_e32 v30, v26
	s_nop 0
	v_pk_mul_f32 v[26:27], v[30:31], v[42:43] op_sel_hi:[0,1]
	v_pk_mul_f32 v[28:29], v[30:31], v[44:45] op_sel_hi:[0,1]
	s_nop 1
	v_mfma_f32_16x16x32_bf16 v[22:25], v[22:25], v[14:17], v[26:29]
	v_mfma_f32_16x16x32_bf16 v[42:45], v[18:21], v[10:13], v[22:25]
	v_mul_f32_e64 v20, v30, v48
	v_mul_f32_e64 v21, v30, v49
	s_nop 5
	v_cvt_pk_bf16_f32 v18, v42, s0
	ds_write_b16 v145, v18 offset:8704
	v_cvt_pk_bf16_f32 v18, v43, s0
	ds_write_b16 v144, v18 offset:8704
	v_cvt_pk_bf16_f32 v18, v44, s0
	ds_write_b16 v144, v18 offset:8976
	v_cvt_pk_bf16_f32 v18, v45, s0
	ds_write_b16 v144, v18 offset:9248
	v_pk_mul_f32 v[18:19], v[30:31], v[46:47] op_sel_hi:[0,1]
	s_nop 1
	v_mfma_f32_16x16x32_bf16 v[6:9], v[6:9], v[14:17], v[18:21]
	v_mfma_f32_16x16x32_bf16 v[46:49], v[2:5], v[10:13], v[6:9]
	s_nop 7
	v_cvt_pk_bf16_f32 v2, v46, s0
	ds_write_b16 v144, v2 offset:12784
	v_cvt_pk_bf16_f32 v2, v47, s0
	ds_write_b16 v144, v2 offset:13056
	v_cvt_pk_bf16_f32 v2, v48, s0
	ds_write_b16 v144, v2 offset:13328
	v_cvt_pk_bf16_f32 v2, v49, s0
	s_add_i32 s0, s76, -1
	s_min_u32 s0, s0, s15
	s_lshl_b32 s0, s0, 6
	s_add_i32 s72, s0, s92
	s_mul_i32 s0, s72, 0x1c00
	s_mul_hi_u32 s1, s72, 0x1c00
	s_add_u32 s0, s36, s0
	s_addc_u32 s1, s37, s1
	ds_write_b16 v144, v2 offset:13600
	v_lshl_add_u64 v[2:3], s[0:1], 0, v[94:95]
	global_load_dwordx4 v[38:41], v[2:3], off
	global_load_dwordx4 v[34:37], v[2:3], off offset:16
	global_load_dwordx4 v[30:33], v[2:3], off offset:128
	global_load_dwordx4 v[26:29], v[2:3], off offset:144
	v_lshl_add_u64 v[2:3], s[0:1], 0, v[92:93]
	global_load_dwordx4 v[22:25], v[2:3], off
	global_load_dwordx4 v[18:21], v[2:3], off offset:16
	v_lshl_add_u64 v[4:5], v[2:3], 0, s[70:71]
	v_add_co_u32_e32 v2, vcc, s94, v2
	s_lshl_b64 s[2:3], s[72:73], 5
	s_lshl_b64 s[56:57], s[72:73], 11
	v_addc_co_u32_e32 v3, vcc, 0, v3, vcc
	v_lshl_add_u64 v[146:147], s[0:1], 0, v[98:99]
	s_add_u32 s2, s78, s2
	v_add_co_u32_e32 v118, vcc, s62, v146
	v_lshl_add_u64 v[10:11], s[0:1], 0, v[96:97]
	s_addc_u32 s3, s79, s3
	v_lshl_add_u64 v[116:117], v[102:103], 0, s[56:57]
	v_addc_co_u32_e32 v119, vcc, 0, v147, vcc
	global_load_dwordx4 v[6:9], v[2:3], off
	s_nop 0
	global_load_dwordx4 v[2:5], v[4:5], off offset:16
	s_nop 0
	global_load_dwordx4 v[14:17], v[10:11], off
	s_nop 0
	global_load_dwordx4 v[10:13], v[10:11], off offset:16
	v_lshl_add_u64 v[148:149], s[2:3], 0, v[100:101]
	global_load_ushort v129, v[116:117], off
	global_load_ushort v128, v[146:147], off
	global_load_dword v130, v[148:149], off
	global_load_ushort v125, v[116:117], off offset:2048
	v_add_co_u32_e32 v116, vcc, s62, v116
	s_add_u32 s0, s2, s14
	s_nop 0
	v_addc_co_u32_e32 v117, vcc, 0, v117, vcc
	v_add_co_u32_e32 v150, vcc, s60, v146
	s_addc_u32 s1, s3, 0
	s_nop 0
	v_addc_co_u32_e32 v151, vcc, 0, v147, vcc
	v_add_co_u32_e32 v146, vcc, s61, v146
	global_load_ushort v126, v[118:119], off offset:3072
	global_load_dword v127, v[148:149], off offset:32
	v_addc_co_u32_e32 v147, vcc, 0, v147, vcc
	global_load_ushort v119, v[116:117], off
	global_load_ushort v120, v[150:151], off offset:2048
	global_load_dword v123, v[148:149], off offset:64
	s_nop 0
	global_load_ushort v116, v[116:117], off offset:2048
	s_nop 0
	global_load_ushort v117, v[146:147], off offset:1024
	global_load_dword v118, v[148:149], off offset:96
	global_load_dword v112, v1, s[0:1] offset:2016
	s_waitcnt lgkmcnt(0)
	s_barrier
; #define LBAR() do { asm volatile("s_waitcnt lgkmcnt(0)" ::: "memory"); __builtin_amdgcn_s_barrier(); asm volatile("" ::: "memory"); } while (0)
; #define LBAR() do { asm volatile("s_waitcnt lgkmcnt(0)" ::: "memory"); __builtin_amdgcn_s_barrier(); asm volatile("" ::: "memory"); } while (0)
; __device__ void ssd_seq(const KP& p, int l, int s, int h, int ph) {
;     ...
; #pragma unroll
;   for (int k = 0; k < 2; ++k) SSD_LOAD(k, row0 + min(k, nch - 1) * 64);
;   int c0 = 0;
;   for (; c0 + 1 < nch; c0 += 2) {
; #pragma unroll
;     for (int k = 0; k < 2; ++k) {
;       const int c = c0 + k;
;       SSD_STEP(k, c);
;       SSD_LOAD(k, row0 + min(c + 2, nch - 1) * 64);
;       LBAR();
	ds_read_b128 v[146:149], v122 offset:8704
	ds_read_b128 v[150:153], v122 offset:8720
	ds_read_b128 v[174:177], v122 offset:8832
	ds_read_b128 v[178:181], v122 offset:8848
	s_waitcnt vmcnt(23) lgkmcnt(3)
	v_mfma_f32_16x16x32_bf16 v[86:89], v[86:89], v[146:149], 0
	s_waitcnt lgkmcnt(2)
	v_mfma_f32_16x16x32_bf16 v[82:85], v[82:85], v[150:153], 0
	s_waitcnt lgkmcnt(1)
	v_mfma_f32_16x16x32_bf16 v[78:81], v[78:81], v[174:177], v[86:89]
	s_waitcnt lgkmcnt(0)
	v_mfma_f32_16x16x32_bf16 v[82:85], v[74:77], v[178:181], v[82:85]
	s_nop 7
	v_pk_add_f32 v[74:75], v[80:81], v[84:85]
	v_mul_f32_e32 v80, 0x3fb8aa3b, v139
	v_exp_f32_e32 v80, v80
	v_pk_add_f32 v[76:77], v[78:79], v[82:83]
	v_lshlrev_b32_e32 v79, 16, v140
	v_add_u32_e32 v78, -3, v124
	v_fmac_f32_e32 v79, v80, v76
	v_lshlrev_b32_e32 v76, 16, v138
	v_mul_f32_e32 v80, 0xbfb8aa3b, v76
	v_exp_f32_e32 v80, v80
	v_cmp_gt_i32_e32 vcc, s86, v78
	v_mul_f32_e32 v78, 0x3fb8aa3b, v137
	v_exp_f32_e32 v78, v78
	v_add_f32_e32 v80, 1.0, v80
	v_rcp_f32_e32 v80, v80
	s_nop 0
	v_mul_f32_e32 v76, v80, v76
	v_mul_f32_e32 v76, v76, v79
	v_cvt_pk_bf16_f32 v76, v76, s0
	v_and_b32_e32 v76, 0xffff, v76
	v_cndmask_b32_e32 v76, 0, v76, vcc
	global_store_short v[104:105], v76, off
	v_lshlrev_b32_e32 v76, 16, v134
	v_fmac_f32_e32 v76, v78, v77
	v_lshlrev_b32_e32 v77, 16, v136
	v_mul_f32_e32 v78, 0xbfb8aa3b, v77
	v_exp_f32_e32 v78, v78
	s_nop 0
	v_add_f32_e32 v78, 1.0, v78
	v_rcp_f32_e32 v78, v78
	s_nop 0
	v_mul_f32_e32 v77, v78, v77
	v_mul_f32_e32 v78, v77, v76
	v_add_u32_e32 v76, -2, v124
	v_cvt_pk_bf16_f32 v78, v78, s0
	v_cmp_gt_i32_e32 vcc, s86, v76
	v_lshl_add_u64 v[76:77], v[104:105], 0, s[58:59]
	v_and_b32_e32 v78, 0xffff, v78
	v_cndmask_b32_e32 v78, 0, v78, vcc
	global_store_short v[76:77], v78, off
	v_mul_f32_e32 v77, 0x3fb8aa3b, v135
	v_exp_f32_e32 v77, v77
	v_lshlrev_b32_e32 v76, 16, v133
	v_fmac_f32_e32 v76, v77, v74
	v_lshlrev_b32_e32 v74, 16, v132
	v_mul_f32_e32 v77, 0xbfb8aa3b, v74
	v_exp_f32_e32 v77, v77
	s_nop 0
	v_add_f32_e32 v77, 1.0, v77
	v_rcp_f32_e32 v77, v77
	s_nop 0
	v_mul_f32_e32 v74, v77, v74
	v_mul_f32_e32 v74, v74, v76
	v_add_u32_e32 v76, -1, v124
	v_cvt_pk_bf16_f32 v74, v74, s0
	v_cmp_gt_i32_e32 vcc, s86, v76
	v_lshl_add_u64 v[76:77], v[104:105], 0, s[64:65]
	v_and_b32_e32 v74, 0xffff, v74
	v_cndmask_b32_e32 v74, 0, v74, vcc
	global_store_short v[76:77], v74, off
	v_mul_f32_e32 v76, 0x3fb8aa3b, v142
	v_exp_f32_e32 v76, v76
	v_lshlrev_b32_e32 v74, 16, v131
	v_cmp_gt_i32_e32 vcc, s86, v124
	v_add_u32_e32 v124, 0x80, v124
	v_fmac_f32_e32 v74, v76, v75
	v_lshlrev_b32_e32 v75, 16, v141
	v_mul_f32_e32 v76, 0xbfb8aa3b, v75
	v_exp_f32_e32 v76, v76
	s_nop 0
	v_add_f32_e32 v76, 1.0, v76
	v_rcp_f32_e32 v76, v76
	s_nop 0
	v_mul_f32_e32 v75, v76, v75
	v_mul_f32_e32 v76, v75, v74
	v_cvt_pk_bf16_f32 v76, v76, s0
	v_lshl_add_u64 v[74:75], v[104:105], 0, s[80:81]
	v_and_b32_e32 v76, 0xffff, v76
	v_cndmask_b32_e32 v76, 0, v76, vcc
	global_store_short v[74:75], v76, off
	v_mul_f32_e32 v74, 0x3fb8aa3b, v143
	v_exp_f32_e32 v74, v74
	s_nop 0
	v_pk_mul_f32 v[44:45], v[74:75], v[44:45] op_sel_hi:[0,1]
	v_pk_mul_f32 v[42:43], v[74:75], v[42:43] op_sel_hi:[0,1]
	v_pk_mul_f32 v[48:49], v[74:75], v[48:49] op_sel_hi:[0,1]
	v_pk_mul_f32 v[46:47], v[74:75], v[46:47] op_sel_hi:[0,1]
	v_mfma_f32_16x16x32_bf16 v[42:45], v[62:65], v[70:73], v[42:45]
	s_nop 0
	v_mfma_f32_16x16x32_bf16 v[46:49], v[54:57], v[70:73], v[46:49]
	v_mfma_f32_16x16x32_bf16 v[42:45], v[58:61], v[66:69], v[42:45]
	v_mfma_f32_16x16x32_bf16 v[46:49], v[50:53], v[66:69], v[46:49]
	s_nop 6
	v_cvt_pk_bf16_f32 v58, v42, s0
	v_cvt_pk_bf16_f32 v50, v46, s0
	ds_write_b16 v145, v58
	v_cvt_pk_bf16_f32 v58, v43, s0
	ds_write_b16 v144, v50 offset:4080
	v_cvt_pk_bf16_f32 v50, v47, s0
	ds_write_b16 v144, v58
	v_cvt_pk_bf16_f32 v58, v44, s0
	ds_write_b16 v144, v50 offset:4352
	v_cvt_pk_bf16_f32 v50, v48, s0
	ds_write_b16 v144, v58 offset:272
	v_cvt_pk_bf16_f32 v58, v45, s0
	ds_write_b16 v144, v50 offset:4624
	v_cvt_pk_bf16_f32 v50, v49, s0
	s_min_u32 s0, s76, s15
	s_lshl_b32 s0, s0, 6
	s_add_i32 s72, s0, s92
	s_mul_i32 s1, s72, 0x1c00
	s_mul_hi_u32 s0, s72, 0x1c00
	s_add_u32 s74, s36, s1
	s_addc_u32 s75, s37, s0
	ds_write_b16 v144, v58 offset:544
	ds_write_b16 v144, v50 offset:4896
	v_lshl_add_u64 v[50:51], s[74:75], 0, v[94:95]
	global_load_dwordx4 v[86:89], v[50:51], off
	global_load_dwordx4 v[82:85], v[50:51], off offset:16
	global_load_dwordx4 v[78:81], v[50:51], off offset:128
	global_load_dwordx4 v[74:77], v[50:51], off offset:144
	v_lshl_add_u64 v[50:51], s[74:75], 0, v[92:93]
	global_load_dwordx4 v[62:65], v[50:51], off
	global_load_dwordx4 v[58:61], v[50:51], off offset:16
	v_lshl_add_u64 v[52:53], v[50:51], 0, s[70:71]
	v_add_co_u32_e32 v50, vcc, s94, v50
	v_lshl_add_u64 v[142:143], s[74:75], 0, v[98:99]
	s_nop 0
	v_addc_co_u32_e32 v51, vcc, 0, v51, vcc
	s_lshl_b64 s[2:3], s[72:73], 11
	v_add_co_u32_e32 v136, vcc, s62, v142
	v_lshl_add_u64 v[132:133], v[102:103], 0, s[2:3]
	s_nop 0
	v_addc_co_u32_e32 v137, vcc, 0, v143, vcc
	v_add_co_u32_e32 v146, vcc, s62, v132
	s_lshl_b64 s[0:1], s[72:73], 5
	s_nop 0
	v_addc_co_u32_e32 v147, vcc, 0, v133, vcc
	s_add_u32 s0, s78, s0
	v_add_co_u32_e32 v148, vcc, s60, v142
	v_lshl_add_u64 v[66:67], s[74:75], 0, v[96:97]
	s_addc_u32 s1, s79, s1
	v_addc_co_u32_e32 v149, vcc, 0, v143, vcc
	global_load_dwordx4 v[54:57], v[50:51], off
	s_nop 0
	global_load_dwordx4 v[50:53], v[52:53], off offset:16
	s_nop 0
	global_load_dwordx4 v[70:73], v[66:67], off
	s_nop 0
	global_load_dwordx4 v[66:69], v[66:67], off offset:16
	v_lshl_add_u64 v[144:145], s[0:1], 0, v[100:101]
	global_load_ushort v140, v[132:133], off
	global_load_ushort v138, v[142:143], off
	global_load_dword v139, v[144:145], off
	global_load_ushort v134, v[132:133], off offset:2048
	v_add_co_u32_e32 v142, vcc, s61, v142
	s_add_u32 s0, s0, s14
	global_load_ushort v136, v[136:137], off offset:3072
	s_nop 0
	global_load_dword v137, v[144:145], off offset:32
	global_load_ushort v133, v[146:147], off
	global_load_ushort v132, v[148:149], off offset:2048
	global_load_dword v135, v[144:145], off offset:64
	global_load_ushort v131, v[146:147], off offset:2048
	v_addc_co_u32_e32 v143, vcc, 0, v143, vcc
	s_addc_u32 s1, s1, 0
	global_load_ushort v141, v[142:143], off offset:1024
	s_nop 0
	global_load_dword v142, v[144:145], off offset:96
	global_load_dword v143, v1, s[0:1] offset:2016
	s_waitcnt lgkmcnt(0)
	s_barrier
	s_add_i32 s0, s76, 2
	s_mov_b64 s[2:3], 0x40000
	v_lshl_add_u64 v[104:105], v[104:105], 0, s[2:3]
	s_cmp_lt_u32 s76, s87
	s_cbranch_scc1 .LBB0_404
	s_add_i32 s3, s0, -3
	s_mov_b64 s[70:71], 0x17ca9100
; #define LBAR() do { asm volatile("s_waitcnt lgkmcnt(0)" ::: "memory"); __builtin_amdgcn_s_barrier(); asm volatile("" ::: "memory"); } while (0)
; #define LBAR() do { asm volatile("s_waitcnt lgkmcnt(0)" ::: "memory"); __builtin_amdgcn_s_barrier(); asm volatile("" ::: "memory"); } while (0)
; __device__ void ssd_seq(const KP& p, int l, int s, int h, int ph) {
;     ...
; #pragma unroll
;   for (int k = 0; k < 2; ++k) SSD_LOAD(k, row0 + min(k, nch - 1) * 64);
;   int c0 = 0;
;   for (; c0 + 1 < nch; c0 += 2) {
; #pragma unroll
;     for (int k = 0; k < 2; ++k) {
;       const int c = c0 + k;
;       SSD_STEP(k, c);
;       SSD_LOAD(k, row0 + min(c + 2, nch - 1) * 64);
;       LBAR();
;     }
;   }
;   if (c0 < nch) { SSD_STEP(0, c0); LBAR(); }
.LBB0_406:
	s_cmp_ge_u32 s3, s87
	s_cbranch_scc1 .LBB0_321
	s_waitcnt vmcnt(16)
	v_add3_u32 v54, v115, v113, v114
	s_waitcnt vmcnt(15)
	ds_read_b128 v[50:53], v54
	s_lshl_b32 s0, s3, 6
	s_add_i32 s72, s0, s92
	s_waitcnt lgkmcnt(0)
	v_mfma_f32_16x16x32_bf16 v[38:41], v[38:41], v[50:53], 0
	ds_read_b128 v[50:53], v54 offset:16
	s_waitcnt lgkmcnt(0)
	v_mfma_f32_16x16x32_bf16 v[34:37], v[34:37], v[50:53], 0
	ds_read_b128 v[50:53], v54 offset:128
	s_waitcnt lgkmcnt(0)
	v_mfma_f32_16x16x32_bf16 v[30:33], v[30:33], v[50:53], v[38:41]
	s_nop 2
	ds_read_b128 v[38:41], v54 offset:144
	s_waitcnt lgkmcnt(0)
	v_mfma_f32_16x16x32_bf16 v[26:29], v[26:29], v[38:41], v[34:37]
	s_nop 7
	v_pk_add_f32 v[28:29], v[32:33], v[28:29]
	s_waitcnt vmcnt(12)
	v_lshlrev_b32_e32 v33, 16, v128
	v_pk_add_f32 v[26:27], v[30:31], v[26:27]
	v_mul_f32_e32 v30, 0xbfb8aa3b, v33
	v_exp_f32_e32 v30, v30
	s_waitcnt vmcnt(4)
	v_mul_f32_e32 v31, 0x3fb8aa3b, v130
	v_add_u32_e32 v32, s0, v111
	s_lshl_b64 s[0:1], s[72:73], 11
	v_add_f32_e32 v30, 1.0, v30
	v_exp_f32_e32 v34, v31
	v_rcp_f32_e32 v35, v30
	s_add_u32 s0, s42, s0
	s_addc_u32 s1, s43, s1
	v_lshl_add_u64 v[30:31], s[0:1], 0, v[0:1]
	v_lshlrev_b32_e32 v0, 16, v129
	v_fmac_f32_e32 v0, v34, v26
	v_mul_f32_e32 v26, v35, v33
	v_mul_f32_e32 v0, v26, v0
	v_lshlrev_b32_e32 v26, 16, v126
	v_mul_f32_e32 v33, 0xbfb8aa3b, v26
	v_exp_f32_e32 v33, v33
	s_waitcnt vmcnt(3)
	v_mul_f32_e32 v34, 0x3fb8aa3b, v127
	v_cvt_pk_bf16_f32 v0, v0, s0
	v_exp_f32_e32 v34, v34
	v_and_b32_e32 v0, 0xffff, v0
	v_cmp_gt_i32_e32 vcc, s86, v32
	v_add_f32_e32 v33, 1.0, v33
	v_rcp_f32_e32 v33, v33
	v_cndmask_b32_e32 v0, 0, v0, vcc
	global_store_short v[30:31], v0, off
	v_lshlrev_b32_e32 v0, 16, v125
	v_fmac_f32_e32 v0, v34, v27
	v_lshlrev_b32_e32 v34, 16, v120
	v_mul_f32_e32 v35, 0xbfb8aa3b, v34
	v_exp_f32_e32 v35, v35
	v_mul_f32_e32 v26, v33, v26
	v_or_b32_e32 v33, 1, v32
	v_mul_f32_e32 v0, v26, v0
	s_mov_b64 s[0:1], 0x800
	v_cmp_gt_i32_e32 vcc, s86, v33
	s_waitcnt vmcnt(2)
	v_mul_f32_e32 v33, 0x3fb8aa3b, v123
	v_cvt_pk_bf16_f32 v0, v0, s0
	v_exp_f32_e32 v33, v33
	v_add_f32_e32 v35, 1.0, v35
	v_and_b32_e32 v0, 0xffff, v0
	v_rcp_f32_e32 v35, v35
	v_cndmask_b32_e32 v0, 0, v0, vcc
	v_lshl_add_u64 v[26:27], v[30:31], 0, s[0:1]
	global_store_short v[26:27], v0, off
	v_lshlrev_b32_e32 v0, 16, v119
	v_fmac_f32_e32 v0, v33, v28
	v_lshlrev_b32_e32 v33, 16, v117
	v_mul_f32_e32 v26, v35, v34
	v_mul_f32_e32 v34, 0xbfb8aa3b, v33
	v_exp_f32_e32 v34, v34
	v_or_b32_e32 v28, 2, v32
	v_mul_f32_e32 v0, v26, v0
	s_mov_b64 s[0:1], 0x1000
	v_cmp_gt_i32_e32 vcc, s86, v28
	s_waitcnt vmcnt(1)
	v_mul_f32_e32 v28, 0x3fb8aa3b, v118
	v_add_f32_e32 v34, 1.0, v34
	v_cvt_pk_bf16_f32 v0, v0, s0
	v_exp_f32_e32 v28, v28
	v_rcp_f32_e32 v34, v34
	v_and_b32_e32 v0, 0xffff, v0
	v_cndmask_b32_e32 v0, 0, v0, vcc
	v_lshl_add_u64 v[26:27], v[30:31], 0, s[0:1]
	global_store_short v[26:27], v0, off
	v_lshlrev_b32_e32 v0, 16, v116
	v_fmac_f32_e32 v0, v28, v29
	v_mul_f32_e32 v26, v34, v33
	v_mul_f32_e32 v26, v26, v0
	s_waitcnt vmcnt(0)
	v_mul_f32_e32 v0, 0x3fb8aa3b, v112
	v_exp_f32_e32 v0, v0
	s_mov_b64 s[0:1], 0x1800
	v_cvt_pk_bf16_f32 v26, v26, s0
	v_and_b32_e32 v33, 0xffff, v26
	v_pk_mul_f32 v[26:27], v[0:1], v[42:43] op_sel_hi:[0,1]
	v_pk_mul_f32 v[28:29], v[0:1], v[44:45] op_sel_hi:[0,1]
	v_or_b32_e32 v32, 3, v32
	v_cmp_gt_i32_e32 vcc, s86, v32
	v_mfma_f32_16x16x32_bf16 v[22:25], v[22:25], v[14:17], v[26:29]
	v_lshl_add_u64 v[30:31], v[30:31], 0, s[0:1]
	v_mfma_f32_16x16x32_bf16 v[42:45], v[18:21], v[10:13], v[22:25]
	v_add_u32_e32 v19, 0, v108
	v_add3_u32 v19, v19, v109, v110
	v_cndmask_b32_e32 v26, 0, v33, vcc
	global_store_short v[30:31], v26, off
	v_pk_mul_f32 v[20:21], v[0:1], v[48:49] op_sel_hi:[0,1]
	s_nop 3
	v_cvt_pk_bf16_f32 v18, v42, s0
	ds_write_b16 v19, v18 offset:8704
	v_add_u32_e32 v19, 0, v106
	v_cvt_pk_bf16_f32 v18, v43, s0
	v_add3_u32 v22, v19, v109, v110
	ds_write_b16 v22, v18 offset:8704
	v_pk_mul_f32 v[18:19], v[0:1], v[46:47] op_sel_hi:[0,1]
	v_cvt_pk_bf16_f32 v0, v45, s0
	ds_write_b16 v22, v0 offset:9248
	v_mfma_f32_16x16x32_bf16 v[6:9], v[6:9], v[14:17], v[18:21]
	v_cvt_pk_bf16_f32 v23, v44, s0
	ds_write_b16 v22, v23 offset:8976
	v_mfma_f32_16x16x32_bf16 v[46:49], v[2:5], v[10:13], v[6:9]
	s_nop 7
	v_cvt_pk_bf16_f32 v0, v46, s0
	ds_write_b16 v22, v0 offset:12784
	v_cvt_pk_bf16_f32 v0, v47, s0
	ds_write_b16 v22, v0 offset:13056
	v_cvt_pk_bf16_f32 v0, v48, s0
	ds_write_b16 v22, v0 offset:13328
	v_cvt_pk_bf16_f32 v0, v49, s0
	ds_write_b16 v22, v0 offset:13600
	s_waitcnt lgkmcnt(0)
	s_barrier
	s_branch .LBB0_321
